# merge phase: three shallow GEMM loops replaced by register-lean LDS-DMA loops
# speedup vs baseline: 1.1318x; 1.0103x over previous
.LBB0_92:
	v_lshrrev_b32_e32 v2, 6, v177
	v_lshlrev_b32_e32 v3, 4, v177
	v_bfe_u32 v0, v177, 3, 3
	v_and_b32_e32 v3, 0x70, v3
	v_and_b32_e32 v4, 8, v2
	v_or3_b32 v185, v3, v4, v0
	v_ashrrev_i32_e32 v0, 7, v177
	v_bfi_b32 v104, -8, v0, v2
	v_mov_b64_e32 v[2:3], s[48:49]
	s_mov_b32 s2, 0x24000
	v_mov_b32_e32 v206, v163
	v_mov_b32_e32 v207, v163
	v_mul_u32_u24_e32 v182, 0x24000, v185
	v_mov_b32_e32 v183, v1
	v_mad_i64_i32 v[4:5], s[2:3], v104, s2, v[2:3]
	v_mov_b32_e32 v2, v163
	v_lshl_add_u64 v[98:99], s[82:83], 0, v[182:183]
	s_movk_i32 s4, 0x480
	v_ashrrev_i32_e32 v3, 3, v2
	v_lshlrev_b32_e32 v0, 4, v2
	v_mad_i64_i32 v[6:7], s[2:3], v3, s4, v[98:99]
	v_and_b32_e32 v0, 0x70, v0
	v_mad_i64_i32 v[4:5], s[2:3], v3, s4, v[4:5]
	v_lshl_add_u64 v[100:101], v[6:7], 0, v[0:1]
	s_mov_b32 s2, 0x9000
	v_lshl_add_u64 v[102:103], v[4:5], 0, v[0:1]
	v_and_b32_e32 v66, 7, v163
	v_bfe_u32 v67, v163, 4, 3
	v_xor_b32_e32 v67, v67, v66
	v_sub_u32_e32 v67, v67, v66
	v_lshlrev_b32_e32 v67, 4, v67
	v_lshrrev_b32_e32 v68, 6, v163
	v_lshlrev_b32_e32 v68, 10, v68
	v_readfirstlane_b32 s2, v100
	v_readfirstlane_b32 s3, v101
	v_readfirstlane_b32 s4, v102
	v_readfirstlane_b32 s5, v103
	v_readfirstlane_b32 s6, v68
	s_nop 3
	v_subrev_u32_e32 v105, s2, v100
	v_subrev_u32_e32 v109, s4, v102
	v_add_u32_e32 v105, v105, v67
	v_add_u32_e32 v109, v109, v67
	v_add_u32_e32 v106, 0x9000, v105
	v_add_u32_e32 v130, 0x9000, v109
	v_add_u32_e32 v107, 0x12000, v105
	v_add_u32_e32 v122, 0x12000, v109
	v_add_u32_e32 v108, 0x1b000, v105
	v_add_u32_e32 v123, 0x1b000, v109
	v_lshlrev_b32_e32 v66, 3, v163
	v_lshlrev_b32_e32 v67, 7, v163
	v_and_b32_e32 v68, 0x2000, v67
	v_and_b32_e32 v67, 0x780, v67
	v_and_b32_e32 v125, 64, v66
	v_xor_b32_e32 v66, v66, v163
	v_and_b32_e32 v66, 48, v66
	v_or3_b32 v66, v67, v125, v66
	v_lshlrev_b32_e32 v67, 6, v163
	v_and_b32_e32 v67, 0xffffe000, v67
	v_or_b32_e32 v126, v66, v68
	v_or_b32_e32 v124, v66, v67
	v_xor_b32_e32 v125, 64, v124
	v_xor_b32_e32 v127, 64, v126
	s_mov_b32 m0, s6
	s_nop 0
	global_load_lds_dwordx4 v105, s[2:3]
	s_add_u32 m0, s6, 0x1000
	s_nop 0
	global_load_lds_dwordx4 v106, s[2:3]
	s_add_u32 m0, s6, 0x2000
	s_nop 0
	global_load_lds_dwordx4 v107, s[2:3]
	s_add_u32 m0, s6, 0x3000
	s_nop 0
	global_load_lds_dwordx4 v108, s[2:3]
	s_add_u32 m0, s6, 0x4000
	s_nop 0
	global_load_lds_dwordx4 v109, s[4:5]
	s_add_u32 m0, s6, 0x5000
	s_nop 0
	global_load_lds_dwordx4 v130, s[4:5]
	s_add_u32 m0, s6, 0x6000
	s_nop 0
	global_load_lds_dwordx4 v122, s[4:5]
	s_add_u32 m0, s6, 0x7000
	s_nop 0
	global_load_lds_dwordx4 v123, s[4:5]
	s_add_u32 s2, s2, 0x80
	s_addc_u32 s3, s3, 0
	s_add_u32 s4, s4, 0x80
	s_addc_u32 s5, s5, 0
	s_waitcnt vmcnt(0)
	s_barrier
	ds_read_b128 v[34:37], v126 offset:16384
	ds_read_b128 v[42:45], v126 offset:18432
	ds_read_b128 v[50:53], v126 offset:20480
	ds_read_b128 v[58:61], v126 offset:22528
	ds_read_b128 v[110:113], v124
	ds_read_b128 v[114:117], v124 offset:2048
	s_add_u32 m0, s6, 0x8000
	s_waitcnt lgkmcnt(1)
	v_mfma_f32_16x16x32_bf16 v[94:97], v[34:37], v[110:113], 0
	v_mfma_f32_16x16x32_bf16 v[86:89], v[42:45], v[110:113], 0
	v_mfma_f32_16x16x32_bf16 v[78:81], v[50:53], v[110:113], 0
	v_mfma_f32_16x16x32_bf16 v[70:73], v[58:61], v[110:113], 0
	ds_read_b128 v[118:121], v124 offset:4096
	ds_read_b128 v[66:69], v127 offset:16384
	ds_read_b128 v[74:77], v127 offset:18432
	ds_read_b128 v[82:85], v127 offset:20480
	ds_read_b128 v[90:93], v127 offset:22528
	global_load_lds_dwordx4 v105, s[2:3]
	s_add_u32 m0, s6, 0x9000
	s_waitcnt lgkmcnt(5)
	v_mfma_f32_16x16x32_bf16 v[62:65], v[34:37], v[114:117], 0
	v_mfma_f32_16x16x32_bf16 v[54:57], v[42:45], v[114:117], 0
	v_mfma_f32_16x16x32_bf16 v[46:49], v[50:53], v[114:117], 0
	v_mfma_f32_16x16x32_bf16 v[38:41], v[58:61], v[114:117], 0
	ds_read_b128 v[110:113], v124 offset:6144
	global_load_lds_dwordx4 v106, s[2:3]
	s_add_u32 m0, s6, 0xa000
	s_waitcnt lgkmcnt(5)
	v_mfma_f32_16x16x32_bf16 v[30:33], v[34:37], v[118:121], 0
	v_mfma_f32_16x16x32_bf16 v[26:29], v[42:45], v[118:121], 0
	v_mfma_f32_16x16x32_bf16 v[22:25], v[50:53], v[118:121], 0
	v_mfma_f32_16x16x32_bf16 v[18:21], v[58:61], v[118:121], 0
	ds_read_b128 v[114:117], v125
	global_load_lds_dwordx4 v107, s[2:3]
	s_add_u32 m0, s6, 0xb000
	s_waitcnt lgkmcnt(1)
	v_mfma_f32_16x16x32_bf16 v[14:17], v[34:37], v[110:113], 0
	v_mfma_f32_16x16x32_bf16 v[10:13], v[42:45], v[110:113], 0
	v_mfma_f32_16x16x32_bf16 v[6:9], v[50:53], v[110:113], 0
	v_mfma_f32_16x16x32_bf16 v[2:5], v[58:61], v[110:113], 0
	ds_read_b128 v[118:121], v125 offset:2048
	global_load_lds_dwordx4 v108, s[2:3]
	s_add_u32 m0, s6, 0xc000
	s_waitcnt lgkmcnt(1)
	v_mfma_f32_16x16x32_bf16 v[94:97], v[66:69], v[114:117], v[94:97]
	v_mfma_f32_16x16x32_bf16 v[86:89], v[74:77], v[114:117], v[86:89]
	v_mfma_f32_16x16x32_bf16 v[78:81], v[82:85], v[114:117], v[78:81]
	v_mfma_f32_16x16x32_bf16 v[70:73], v[90:93], v[114:117], v[70:73]
	ds_read_b128 v[110:113], v125 offset:4096
	global_load_lds_dwordx4 v109, s[4:5]
	s_add_u32 m0, s6, 0xd000
	s_waitcnt lgkmcnt(1)
	v_mfma_f32_16x16x32_bf16 v[62:65], v[66:69], v[118:121], v[62:65]
	v_mfma_f32_16x16x32_bf16 v[54:57], v[74:77], v[118:121], v[54:57]
	v_mfma_f32_16x16x32_bf16 v[46:49], v[82:85], v[118:121], v[46:49]
	v_mfma_f32_16x16x32_bf16 v[38:41], v[90:93], v[118:121], v[38:41]
	ds_read_b128 v[114:117], v125 offset:6144
	global_load_lds_dwordx4 v130, s[4:5]
	s_add_u32 m0, s6, 0xe000
	s_waitcnt lgkmcnt(1)
	v_mfma_f32_16x16x32_bf16 v[30:33], v[66:69], v[110:113], v[30:33]
	v_mfma_f32_16x16x32_bf16 v[26:29], v[74:77], v[110:113], v[26:29]
	v_mfma_f32_16x16x32_bf16 v[22:25], v[82:85], v[110:113], v[22:25]
	v_mfma_f32_16x16x32_bf16 v[18:21], v[90:93], v[110:113], v[18:21]
	global_load_lds_dwordx4 v122, s[4:5]
	s_add_u32 m0, s6, 0xf000
	s_waitcnt lgkmcnt(0)
	v_mfma_f32_16x16x32_bf16 v[14:17], v[66:69], v[114:117], v[14:17]
	v_mfma_f32_16x16x32_bf16 v[10:13], v[74:77], v[114:117], v[10:13]
	v_mfma_f32_16x16x32_bf16 v[6:9], v[82:85], v[114:117], v[6:9]
	v_mfma_f32_16x16x32_bf16 v[2:5], v[90:93], v[114:117], v[2:5]
	global_load_lds_dwordx4 v123, s[4:5]
	s_add_u32 s2, s2, 0x80
	s_addc_u32 s3, s3, 0
	s_add_u32 s4, s4, 0x80
	s_addc_u32 s5, s5, 0
	s_waitcnt vmcnt(0) lgkmcnt(0)
	s_barrier
	ds_read_b128 v[34:37], v126 offset:49152
	ds_read_b128 v[42:45], v126 offset:51200
	ds_read_b128 v[50:53], v126 offset:53248
	ds_read_b128 v[58:61], v126 offset:55296
	ds_read_b128 v[110:113], v124 offset:32768
	ds_read_b128 v[114:117], v124 offset:34816
	s_mov_b32 m0, s6
	s_waitcnt lgkmcnt(1)
	v_mfma_f32_16x16x32_bf16 v[94:97], v[34:37], v[110:113], v[94:97]
	v_mfma_f32_16x16x32_bf16 v[86:89], v[42:45], v[110:113], v[86:89]
	v_mfma_f32_16x16x32_bf16 v[78:81], v[50:53], v[110:113], v[78:81]
	v_mfma_f32_16x16x32_bf16 v[70:73], v[58:61], v[110:113], v[70:73]
	ds_read_b128 v[118:121], v124 offset:36864
	ds_read_b128 v[66:69], v127 offset:49152
	ds_read_b128 v[74:77], v127 offset:51200
	ds_read_b128 v[82:85], v127 offset:53248
	ds_read_b128 v[90:93], v127 offset:55296
	global_load_lds_dwordx4 v105, s[2:3]
	s_add_u32 m0, s6, 0x1000
	s_waitcnt lgkmcnt(5)
	v_mfma_f32_16x16x32_bf16 v[62:65], v[34:37], v[114:117], v[62:65]
	v_mfma_f32_16x16x32_bf16 v[54:57], v[42:45], v[114:117], v[54:57]
	v_mfma_f32_16x16x32_bf16 v[46:49], v[50:53], v[114:117], v[46:49]
	v_mfma_f32_16x16x32_bf16 v[38:41], v[58:61], v[114:117], v[38:41]
	ds_read_b128 v[110:113], v124 offset:38912
	global_load_lds_dwordx4 v106, s[2:3]
	s_add_u32 m0, s6, 0x2000
	s_waitcnt lgkmcnt(5)
	v_mfma_f32_16x16x32_bf16 v[30:33], v[34:37], v[118:121], v[30:33]
	v_mfma_f32_16x16x32_bf16 v[26:29], v[42:45], v[118:121], v[26:29]
	v_mfma_f32_16x16x32_bf16 v[22:25], v[50:53], v[118:121], v[22:25]
	v_mfma_f32_16x16x32_bf16 v[18:21], v[58:61], v[118:121], v[18:21]
	ds_read_b128 v[114:117], v125 offset:32768
	global_load_lds_dwordx4 v107, s[2:3]
	s_add_u32 m0, s6, 0x3000
	s_waitcnt lgkmcnt(1)
	v_mfma_f32_16x16x32_bf16 v[14:17], v[34:37], v[110:113], v[14:17]
	v_mfma_f32_16x16x32_bf16 v[10:13], v[42:45], v[110:113], v[10:13]
	v_mfma_f32_16x16x32_bf16 v[6:9], v[50:53], v[110:113], v[6:9]
	v_mfma_f32_16x16x32_bf16 v[2:5], v[58:61], v[110:113], v[2:5]
	ds_read_b128 v[118:121], v125 offset:34816
	global_load_lds_dwordx4 v108, s[2:3]
	s_add_u32 m0, s6, 0x4000
	s_waitcnt lgkmcnt(1)
	v_mfma_f32_16x16x32_bf16 v[94:97], v[66:69], v[114:117], v[94:97]
	v_mfma_f32_16x16x32_bf16 v[86:89], v[74:77], v[114:117], v[86:89]
	v_mfma_f32_16x16x32_bf16 v[78:81], v[82:85], v[114:117], v[78:81]
	v_mfma_f32_16x16x32_bf16 v[70:73], v[90:93], v[114:117], v[70:73]
	ds_read_b128 v[110:113], v125 offset:36864
	global_load_lds_dwordx4 v109, s[4:5]
	s_add_u32 m0, s6, 0x5000
	s_waitcnt lgkmcnt(1)
	v_mfma_f32_16x16x32_bf16 v[62:65], v[66:69], v[118:121], v[62:65]
	v_mfma_f32_16x16x32_bf16 v[54:57], v[74:77], v[118:121], v[54:57]
	v_mfma_f32_16x16x32_bf16 v[46:49], v[82:85], v[118:121], v[46:49]
	v_mfma_f32_16x16x32_bf16 v[38:41], v[90:93], v[118:121], v[38:41]
	ds_read_b128 v[114:117], v125 offset:38912
	global_load_lds_dwordx4 v130, s[4:5]
	s_add_u32 m0, s6, 0x6000
	s_waitcnt lgkmcnt(1)
	v_mfma_f32_16x16x32_bf16 v[30:33], v[66:69], v[110:113], v[30:33]
	v_mfma_f32_16x16x32_bf16 v[26:29], v[74:77], v[110:113], v[26:29]
	v_mfma_f32_16x16x32_bf16 v[22:25], v[82:85], v[110:113], v[22:25]
	v_mfma_f32_16x16x32_bf16 v[18:21], v[90:93], v[110:113], v[18:21]
	global_load_lds_dwordx4 v122, s[4:5]
	s_add_u32 m0, s6, 0x7000
	s_waitcnt lgkmcnt(0)
	v_mfma_f32_16x16x32_bf16 v[14:17], v[66:69], v[114:117], v[14:17]
	v_mfma_f32_16x16x32_bf16 v[10:13], v[74:77], v[114:117], v[10:13]
	v_mfma_f32_16x16x32_bf16 v[6:9], v[82:85], v[114:117], v[6:9]
	v_mfma_f32_16x16x32_bf16 v[2:5], v[90:93], v[114:117], v[2:5]
	global_load_lds_dwordx4 v123, s[4:5]
	s_add_u32 s2, s2, 0x80
	s_addc_u32 s3, s3, 0
	s_add_u32 s4, s4, 0x80
	s_addc_u32 s5, s5, 0
	s_waitcnt vmcnt(0) lgkmcnt(0)
	s_barrier
	s_movk_i32 s7, 2
.Lm1_loop:
	ds_read_b128 v[34:37], v126 offset:16384
	ds_read_b128 v[42:45], v126 offset:18432
	ds_read_b128 v[50:53], v126 offset:20480
	ds_read_b128 v[58:61], v126 offset:22528
	ds_read_b128 v[110:113], v124
	ds_read_b128 v[114:117], v124 offset:2048
	s_add_u32 m0, s6, 0x8000
	s_waitcnt lgkmcnt(1)
	v_mfma_f32_16x16x32_bf16 v[94:97], v[34:37], v[110:113], v[94:97]
	v_mfma_f32_16x16x32_bf16 v[86:89], v[42:45], v[110:113], v[86:89]
	v_mfma_f32_16x16x32_bf16 v[78:81], v[50:53], v[110:113], v[78:81]
	v_mfma_f32_16x16x32_bf16 v[70:73], v[58:61], v[110:113], v[70:73]
	ds_read_b128 v[118:121], v124 offset:4096
	ds_read_b128 v[66:69], v127 offset:16384
	ds_read_b128 v[74:77], v127 offset:18432
	ds_read_b128 v[82:85], v127 offset:20480
	ds_read_b128 v[90:93], v127 offset:22528
	global_load_lds_dwordx4 v105, s[2:3]
	s_add_u32 m0, s6, 0x9000
	s_waitcnt lgkmcnt(5)
	v_mfma_f32_16x16x32_bf16 v[62:65], v[34:37], v[114:117], v[62:65]
	v_mfma_f32_16x16x32_bf16 v[54:57], v[42:45], v[114:117], v[54:57]
	v_mfma_f32_16x16x32_bf16 v[46:49], v[50:53], v[114:117], v[46:49]
	v_mfma_f32_16x16x32_bf16 v[38:41], v[58:61], v[114:117], v[38:41]
	ds_read_b128 v[110:113], v124 offset:6144
	global_load_lds_dwordx4 v106, s[2:3]
	s_add_u32 m0, s6, 0xa000
	s_waitcnt lgkmcnt(5)
	v_mfma_f32_16x16x32_bf16 v[30:33], v[34:37], v[118:121], v[30:33]
	v_mfma_f32_16x16x32_bf16 v[26:29], v[42:45], v[118:121], v[26:29]
	v_mfma_f32_16x16x32_bf16 v[22:25], v[50:53], v[118:121], v[22:25]
	v_mfma_f32_16x16x32_bf16 v[18:21], v[58:61], v[118:121], v[18:21]
	ds_read_b128 v[114:117], v125
	global_load_lds_dwordx4 v107, s[2:3]
	s_add_u32 m0, s6, 0xb000
	s_waitcnt lgkmcnt(1)
	v_mfma_f32_16x16x32_bf16 v[14:17], v[34:37], v[110:113], v[14:17]
	v_mfma_f32_16x16x32_bf16 v[10:13], v[42:45], v[110:113], v[10:13]
	v_mfma_f32_16x16x32_bf16 v[6:9], v[50:53], v[110:113], v[6:9]
	v_mfma_f32_16x16x32_bf16 v[2:5], v[58:61], v[110:113], v[2:5]
	ds_read_b128 v[118:121], v125 offset:2048
	global_load_lds_dwordx4 v108, s[2:3]
	s_add_u32 m0, s6, 0xc000
	s_waitcnt lgkmcnt(1)
	v_mfma_f32_16x16x32_bf16 v[94:97], v[66:69], v[114:117], v[94:97]
	v_mfma_f32_16x16x32_bf16 v[86:89], v[74:77], v[114:117], v[86:89]
	v_mfma_f32_16x16x32_bf16 v[78:81], v[82:85], v[114:117], v[78:81]
	v_mfma_f32_16x16x32_bf16 v[70:73], v[90:93], v[114:117], v[70:73]
	ds_read_b128 v[110:113], v125 offset:4096
	global_load_lds_dwordx4 v109, s[4:5]
	s_add_u32 m0, s6, 0xd000
	s_waitcnt lgkmcnt(1)
	v_mfma_f32_16x16x32_bf16 v[62:65], v[66:69], v[118:121], v[62:65]
	v_mfma_f32_16x16x32_bf16 v[54:57], v[74:77], v[118:121], v[54:57]
	v_mfma_f32_16x16x32_bf16 v[46:49], v[82:85], v[118:121], v[46:49]
	v_mfma_f32_16x16x32_bf16 v[38:41], v[90:93], v[118:121], v[38:41]
	ds_read_b128 v[114:117], v125 offset:6144
	global_load_lds_dwordx4 v130, s[4:5]
	s_add_u32 m0, s6, 0xe000
	s_waitcnt lgkmcnt(1)
	v_mfma_f32_16x16x32_bf16 v[30:33], v[66:69], v[110:113], v[30:33]
	v_mfma_f32_16x16x32_bf16 v[26:29], v[74:77], v[110:113], v[26:29]
	v_mfma_f32_16x16x32_bf16 v[22:25], v[82:85], v[110:113], v[22:25]
	v_mfma_f32_16x16x32_bf16 v[18:21], v[90:93], v[110:113], v[18:21]
	global_load_lds_dwordx4 v122, s[4:5]
	s_add_u32 m0, s6, 0xf000
	s_waitcnt lgkmcnt(0)
	v_mfma_f32_16x16x32_bf16 v[14:17], v[66:69], v[114:117], v[14:17]
	v_mfma_f32_16x16x32_bf16 v[10:13], v[74:77], v[114:117], v[10:13]
	v_mfma_f32_16x16x32_bf16 v[6:9], v[82:85], v[114:117], v[6:9]
	v_mfma_f32_16x16x32_bf16 v[2:5], v[90:93], v[114:117], v[2:5]
	global_load_lds_dwordx4 v123, s[4:5]
	s_add_u32 s2, s2, 0x80
	s_addc_u32 s3, s3, 0
	s_add_u32 s4, s4, 0x80
	s_addc_u32 s5, s5, 0
	s_waitcnt vmcnt(0) lgkmcnt(0)
	s_barrier
	ds_read_b128 v[34:37], v126 offset:49152
	ds_read_b128 v[42:45], v126 offset:51200
	ds_read_b128 v[50:53], v126 offset:53248
	ds_read_b128 v[58:61], v126 offset:55296
	ds_read_b128 v[110:113], v124 offset:32768
	ds_read_b128 v[114:117], v124 offset:34816
	s_mov_b32 m0, s6
	s_waitcnt lgkmcnt(1)
	v_mfma_f32_16x16x32_bf16 v[94:97], v[34:37], v[110:113], v[94:97]
	v_mfma_f32_16x16x32_bf16 v[86:89], v[42:45], v[110:113], v[86:89]
	v_mfma_f32_16x16x32_bf16 v[78:81], v[50:53], v[110:113], v[78:81]
	v_mfma_f32_16x16x32_bf16 v[70:73], v[58:61], v[110:113], v[70:73]
	ds_read_b128 v[118:121], v124 offset:36864
	ds_read_b128 v[66:69], v127 offset:49152
	ds_read_b128 v[74:77], v127 offset:51200
	ds_read_b128 v[82:85], v127 offset:53248
	ds_read_b128 v[90:93], v127 offset:55296
	global_load_lds_dwordx4 v105, s[2:3]
	s_add_u32 m0, s6, 0x1000
	s_waitcnt lgkmcnt(5)
	v_mfma_f32_16x16x32_bf16 v[62:65], v[34:37], v[114:117], v[62:65]
	v_mfma_f32_16x16x32_bf16 v[54:57], v[42:45], v[114:117], v[54:57]
	v_mfma_f32_16x16x32_bf16 v[46:49], v[50:53], v[114:117], v[46:49]
	v_mfma_f32_16x16x32_bf16 v[38:41], v[58:61], v[114:117], v[38:41]
	ds_read_b128 v[110:113], v124 offset:38912
	global_load_lds_dwordx4 v106, s[2:3]
	s_add_u32 m0, s6, 0x2000
	s_waitcnt lgkmcnt(5)
	v_mfma_f32_16x16x32_bf16 v[30:33], v[34:37], v[118:121], v[30:33]
	v_mfma_f32_16x16x32_bf16 v[26:29], v[42:45], v[118:121], v[26:29]
	v_mfma_f32_16x16x32_bf16 v[22:25], v[50:53], v[118:121], v[22:25]
	v_mfma_f32_16x16x32_bf16 v[18:21], v[58:61], v[118:121], v[18:21]
	ds_read_b128 v[114:117], v125 offset:32768
	global_load_lds_dwordx4 v107, s[2:3]
	s_add_u32 m0, s6, 0x3000
	s_waitcnt lgkmcnt(1)
	v_mfma_f32_16x16x32_bf16 v[14:17], v[34:37], v[110:113], v[14:17]
	v_mfma_f32_16x16x32_bf16 v[10:13], v[42:45], v[110:113], v[10:13]
	v_mfma_f32_16x16x32_bf16 v[6:9], v[50:53], v[110:113], v[6:9]
	v_mfma_f32_16x16x32_bf16 v[2:5], v[58:61], v[110:113], v[2:5]
	ds_read_b128 v[118:121], v125 offset:34816
	global_load_lds_dwordx4 v108, s[2:3]
	s_add_u32 m0, s6, 0x4000
	s_waitcnt lgkmcnt(1)
	v_mfma_f32_16x16x32_bf16 v[94:97], v[66:69], v[114:117], v[94:97]
	v_mfma_f32_16x16x32_bf16 v[86:89], v[74:77], v[114:117], v[86:89]
	v_mfma_f32_16x16x32_bf16 v[78:81], v[82:85], v[114:117], v[78:81]
	v_mfma_f32_16x16x32_bf16 v[70:73], v[90:93], v[114:117], v[70:73]
	ds_read_b128 v[110:113], v125 offset:36864
	global_load_lds_dwordx4 v109, s[4:5]
	s_add_u32 m0, s6, 0x5000
	s_waitcnt lgkmcnt(1)
	v_mfma_f32_16x16x32_bf16 v[62:65], v[66:69], v[118:121], v[62:65]
	v_mfma_f32_16x16x32_bf16 v[54:57], v[74:77], v[118:121], v[54:57]
	v_mfma_f32_16x16x32_bf16 v[46:49], v[82:85], v[118:121], v[46:49]
	v_mfma_f32_16x16x32_bf16 v[38:41], v[90:93], v[118:121], v[38:41]
	ds_read_b128 v[114:117], v125 offset:38912
	global_load_lds_dwordx4 v130, s[4:5]
	s_add_u32 m0, s6, 0x6000
	s_waitcnt lgkmcnt(1)
	v_mfma_f32_16x16x32_bf16 v[30:33], v[66:69], v[110:113], v[30:33]
	v_mfma_f32_16x16x32_bf16 v[26:29], v[74:77], v[110:113], v[26:29]
	v_mfma_f32_16x16x32_bf16 v[22:25], v[82:85], v[110:113], v[22:25]
	v_mfma_f32_16x16x32_bf16 v[18:21], v[90:93], v[110:113], v[18:21]
	global_load_lds_dwordx4 v122, s[4:5]
	s_add_u32 m0, s6, 0x7000
	s_waitcnt lgkmcnt(0)
	v_mfma_f32_16x16x32_bf16 v[14:17], v[66:69], v[114:117], v[14:17]
	v_mfma_f32_16x16x32_bf16 v[10:13], v[74:77], v[114:117], v[10:13]
	v_mfma_f32_16x16x32_bf16 v[6:9], v[82:85], v[114:117], v[6:9]
	v_mfma_f32_16x16x32_bf16 v[2:5], v[90:93], v[114:117], v[2:5]
	global_load_lds_dwordx4 v123, s[4:5]
	s_add_u32 s2, s2, 0x80
	s_addc_u32 s3, s3, 0
	s_add_u32 s4, s4, 0x80
	s_addc_u32 s5, s5, 0
	s_add_i32 s7, s7, -1
	s_waitcnt vmcnt(0) lgkmcnt(0)
	s_barrier
	s_cmp_lg_u32 s7, 0
	s_cbranch_scc1 .Lm1_loop
	ds_read_b128 v[34:37], v126 offset:16384
	ds_read_b128 v[42:45], v126 offset:18432
	ds_read_b128 v[50:53], v126 offset:20480
	ds_read_b128 v[58:61], v126 offset:22528
	ds_read_b128 v[110:113], v124
	ds_read_b128 v[114:117], v124 offset:2048
	s_add_u32 m0, s6, 0x8000
	s_waitcnt lgkmcnt(1)
	v_mfma_f32_16x16x32_bf16 v[94:97], v[34:37], v[110:113], v[94:97]
	v_mfma_f32_16x16x32_bf16 v[86:89], v[42:45], v[110:113], v[86:89]
	v_mfma_f32_16x16x32_bf16 v[78:81], v[50:53], v[110:113], v[78:81]
	v_mfma_f32_16x16x32_bf16 v[70:73], v[58:61], v[110:113], v[70:73]
	ds_read_b128 v[118:121], v124 offset:4096
	ds_read_b128 v[66:69], v127 offset:16384
	ds_read_b128 v[74:77], v127 offset:18432
	ds_read_b128 v[82:85], v127 offset:20480
	ds_read_b128 v[90:93], v127 offset:22528
	global_load_lds_dwordx4 v105, s[2:3]
	s_add_u32 m0, s6, 0x9000
	s_waitcnt lgkmcnt(5)
	v_mfma_f32_16x16x32_bf16 v[62:65], v[34:37], v[114:117], v[62:65]
	v_mfma_f32_16x16x32_bf16 v[54:57], v[42:45], v[114:117], v[54:57]
	v_mfma_f32_16x16x32_bf16 v[46:49], v[50:53], v[114:117], v[46:49]
	v_mfma_f32_16x16x32_bf16 v[38:41], v[58:61], v[114:117], v[38:41]
	ds_read_b128 v[110:113], v124 offset:6144
	global_load_lds_dwordx4 v106, s[2:3]
	s_add_u32 m0, s6, 0xa000
	s_waitcnt lgkmcnt(5)
	v_mfma_f32_16x16x32_bf16 v[30:33], v[34:37], v[118:121], v[30:33]
	v_mfma_f32_16x16x32_bf16 v[26:29], v[42:45], v[118:121], v[26:29]
	v_mfma_f32_16x16x32_bf16 v[22:25], v[50:53], v[118:121], v[22:25]
	v_mfma_f32_16x16x32_bf16 v[18:21], v[58:61], v[118:121], v[18:21]
	ds_read_b128 v[114:117], v125
	global_load_lds_dwordx4 v107, s[2:3]
	s_add_u32 m0, s6, 0xb000
	s_waitcnt lgkmcnt(1)
	v_mfma_f32_16x16x32_bf16 v[14:17], v[34:37], v[110:113], v[14:17]
	v_mfma_f32_16x16x32_bf16 v[10:13], v[42:45], v[110:113], v[10:13]
	v_mfma_f32_16x16x32_bf16 v[6:9], v[50:53], v[110:113], v[6:9]
	v_mfma_f32_16x16x32_bf16 v[2:5], v[58:61], v[110:113], v[2:5]
	ds_read_b128 v[118:121], v125 offset:2048
	global_load_lds_dwordx4 v108, s[2:3]
	s_add_u32 m0, s6, 0xc000
	s_waitcnt lgkmcnt(1)
	v_mfma_f32_16x16x32_bf16 v[94:97], v[66:69], v[114:117], v[94:97]
	v_mfma_f32_16x16x32_bf16 v[86:89], v[74:77], v[114:117], v[86:89]
	v_mfma_f32_16x16x32_bf16 v[78:81], v[82:85], v[114:117], v[78:81]
	v_mfma_f32_16x16x32_bf16 v[70:73], v[90:93], v[114:117], v[70:73]
	ds_read_b128 v[110:113], v125 offset:4096
	global_load_lds_dwordx4 v109, s[4:5]
	s_add_u32 m0, s6, 0xd000
	s_waitcnt lgkmcnt(1)
	v_mfma_f32_16x16x32_bf16 v[62:65], v[66:69], v[118:121], v[62:65]
	v_mfma_f32_16x16x32_bf16 v[54:57], v[74:77], v[118:121], v[54:57]
	v_mfma_f32_16x16x32_bf16 v[46:49], v[82:85], v[118:121], v[46:49]
	v_mfma_f32_16x16x32_bf16 v[38:41], v[90:93], v[118:121], v[38:41]
	ds_read_b128 v[114:117], v125 offset:6144
	global_load_lds_dwordx4 v130, s[4:5]
	s_add_u32 m0, s6, 0xe000
	s_waitcnt lgkmcnt(1)
	v_mfma_f32_16x16x32_bf16 v[30:33], v[66:69], v[110:113], v[30:33]
	v_mfma_f32_16x16x32_bf16 v[26:29], v[74:77], v[110:113], v[26:29]
	v_mfma_f32_16x16x32_bf16 v[22:25], v[82:85], v[110:113], v[22:25]
	v_mfma_f32_16x16x32_bf16 v[18:21], v[90:93], v[110:113], v[18:21]
	global_load_lds_dwordx4 v122, s[4:5]
	s_add_u32 m0, s6, 0xf000
	s_waitcnt lgkmcnt(0)
	v_mfma_f32_16x16x32_bf16 v[14:17], v[66:69], v[114:117], v[14:17]
	v_mfma_f32_16x16x32_bf16 v[10:13], v[74:77], v[114:117], v[10:13]
	v_mfma_f32_16x16x32_bf16 v[6:9], v[82:85], v[114:117], v[6:9]
	v_mfma_f32_16x16x32_bf16 v[2:5], v[90:93], v[114:117], v[2:5]
	global_load_lds_dwordx4 v123, s[4:5]
	s_add_u32 s2, s2, 0x80
	s_addc_u32 s3, s3, 0
	s_add_u32 s4, s4, 0x80
	s_addc_u32 s5, s5, 0
	s_waitcnt vmcnt(0) lgkmcnt(0)
	s_barrier
	ds_read_b128 v[34:37], v126 offset:49152
	ds_read_b128 v[42:45], v126 offset:51200
	ds_read_b128 v[50:53], v126 offset:53248
	ds_read_b128 v[58:61], v126 offset:55296
	ds_read_b128 v[110:113], v124 offset:32768
	ds_read_b128 v[114:117], v124 offset:34816
	s_waitcnt lgkmcnt(1)
	v_mfma_f32_16x16x32_bf16 v[94:97], v[34:37], v[110:113], v[94:97]
	v_mfma_f32_16x16x32_bf16 v[86:89], v[42:45], v[110:113], v[86:89]
	v_mfma_f32_16x16x32_bf16 v[78:81], v[50:53], v[110:113], v[78:81]
	v_mfma_f32_16x16x32_bf16 v[70:73], v[58:61], v[110:113], v[70:73]
	ds_read_b128 v[118:121], v124 offset:36864
	ds_read_b128 v[66:69], v127 offset:49152
	ds_read_b128 v[74:77], v127 offset:51200
	ds_read_b128 v[82:85], v127 offset:53248
	ds_read_b128 v[90:93], v127 offset:55296
	s_waitcnt lgkmcnt(5)
	v_mfma_f32_16x16x32_bf16 v[62:65], v[34:37], v[114:117], v[62:65]
	v_mfma_f32_16x16x32_bf16 v[54:57], v[42:45], v[114:117], v[54:57]
	v_mfma_f32_16x16x32_bf16 v[46:49], v[50:53], v[114:117], v[46:49]
	v_mfma_f32_16x16x32_bf16 v[38:41], v[58:61], v[114:117], v[38:41]
	ds_read_b128 v[110:113], v124 offset:38912
	s_waitcnt lgkmcnt(5)
	v_mfma_f32_16x16x32_bf16 v[30:33], v[34:37], v[118:121], v[30:33]
	v_mfma_f32_16x16x32_bf16 v[26:29], v[42:45], v[118:121], v[26:29]
	v_mfma_f32_16x16x32_bf16 v[22:25], v[50:53], v[118:121], v[22:25]
	v_mfma_f32_16x16x32_bf16 v[18:21], v[58:61], v[118:121], v[18:21]
	ds_read_b128 v[114:117], v125 offset:32768
	s_waitcnt lgkmcnt(1)
	v_mfma_f32_16x16x32_bf16 v[14:17], v[34:37], v[110:113], v[14:17]
	v_mfma_f32_16x16x32_bf16 v[10:13], v[42:45], v[110:113], v[10:13]
	v_mfma_f32_16x16x32_bf16 v[6:9], v[50:53], v[110:113], v[6:9]
	v_mfma_f32_16x16x32_bf16 v[2:5], v[58:61], v[110:113], v[2:5]
	ds_read_b128 v[118:121], v125 offset:34816
	s_waitcnt lgkmcnt(1)
	v_mfma_f32_16x16x32_bf16 v[94:97], v[66:69], v[114:117], v[94:97]
	v_mfma_f32_16x16x32_bf16 v[86:89], v[74:77], v[114:117], v[86:89]
	v_mfma_f32_16x16x32_bf16 v[78:81], v[82:85], v[114:117], v[78:81]
	v_mfma_f32_16x16x32_bf16 v[70:73], v[90:93], v[114:117], v[70:73]
	ds_read_b128 v[110:113], v125 offset:36864
	s_waitcnt lgkmcnt(1)
	v_mfma_f32_16x16x32_bf16 v[62:65], v[66:69], v[118:121], v[62:65]
	v_mfma_f32_16x16x32_bf16 v[54:57], v[74:77], v[118:121], v[54:57]
	v_mfma_f32_16x16x32_bf16 v[46:49], v[82:85], v[118:121], v[46:49]
	v_mfma_f32_16x16x32_bf16 v[38:41], v[90:93], v[118:121], v[38:41]
	ds_read_b128 v[114:117], v125 offset:38912
	s_waitcnt lgkmcnt(1)
	v_mfma_f32_16x16x32_bf16 v[30:33], v[66:69], v[110:113], v[30:33]
	v_mfma_f32_16x16x32_bf16 v[26:29], v[74:77], v[110:113], v[26:29]
	v_mfma_f32_16x16x32_bf16 v[22:25], v[82:85], v[110:113], v[22:25]
	v_mfma_f32_16x16x32_bf16 v[18:21], v[90:93], v[110:113], v[18:21]
	s_waitcnt lgkmcnt(0)
	v_mfma_f32_16x16x32_bf16 v[14:17], v[66:69], v[114:117], v[14:17]
	v_mfma_f32_16x16x32_bf16 v[10:13], v[74:77], v[114:117], v[10:13]
	v_mfma_f32_16x16x32_bf16 v[6:9], v[82:85], v[114:117], v[6:9]
	v_mfma_f32_16x16x32_bf16 v[2:5], v[90:93], v[114:117], v[2:5]
	s_waitcnt lgkmcnt(0)
	s_barrier
	s_nop 7
	s_nop 2
.LBB0_100:
	v_lshlrev_b32_e32 v184, 7, v104
	s_mov_b32 s2, 0x24000
	v_add_u32_e32 v0, 0x400, v184
	s_waitcnt vmcnt(7)
	v_mov_b64_e32 v[34:35], s[48:49]
	s_movk_i32 s4, 0x480
	v_mad_i64_i32 v[186:187], s[2:3], v104, s2, 0
	v_mad_i64_i32 v[36:37], s[2:3], v0, s4, v[34:35]
	v_mov_b32_e32 v34, v163
	s_mov_b32 s5, 0x1b000
	v_ashrrev_i32_e32 v35, 3, v34
	v_lshlrev_b32_e32 v0, 4, v34
	s_waitcnt vmcnt(6)
	v_mad_i64_i32 v[42:43], s[2:3], v35, s4, v[98:99]
	v_and_b32_e32 v0, 0x70, v0
	v_mad_i64_i32 v[36:37], s[2:3], v35, s4, v[36:37]
	v_lshl_add_u64 v[188:189], v[42:43], 0, v[0:1]
	s_mov_b32 s2, 0x9000
	v_lshl_add_u64 v[190:191], v[36:37], 0, v[0:1]
	v_and_b32_e32 v146, 7, v163
	v_bfe_u32 v147, v163, 4, 3
	v_xor_b32_e32 v147, v147, v146
	v_sub_u32_e32 v147, v147, v146
	v_lshlrev_b32_e32 v147, 4, v147
	v_lshrrev_b32_e32 v148, 6, v163
	v_lshlrev_b32_e32 v148, 10, v148
	v_readfirstlane_b32 s2, v188
	v_readfirstlane_b32 s3, v189
	v_readfirstlane_b32 s4, v190
	v_readfirstlane_b32 s5, v191
	v_readfirstlane_b32 s6, v148
	s_nop 3
	v_subrev_u32_e32 v220, s2, v188
	v_subrev_u32_e32 v224, s4, v190
	v_add_u32_e32 v220, v220, v147
	v_add_u32_e32 v224, v224, v147
	v_add_u32_e32 v221, 0x9000, v220
	v_add_u32_e32 v225, 0x9000, v224
	v_add_u32_e32 v222, 0x12000, v220
	v_add_u32_e32 v226, 0x12000, v224
	v_add_u32_e32 v223, 0x1b000, v220
	v_add_u32_e32 v227, 0x1b000, v224
	v_lshlrev_b32_e32 v146, 3, v163
	v_lshlrev_b32_e32 v147, 7, v163
	v_and_b32_e32 v148, 0x2000, v147
	v_and_b32_e32 v147, 0x780, v147
	v_and_b32_e32 v229, 64, v146
	v_xor_b32_e32 v146, v146, v163
	v_and_b32_e32 v146, 48, v146
	v_or3_b32 v146, v147, v229, v146
	v_lshlrev_b32_e32 v147, 6, v163
	v_and_b32_e32 v147, 0xffffe000, v147
	v_or_b32_e32 v230, v146, v148
	v_or_b32_e32 v228, v146, v147
	v_xor_b32_e32 v229, 64, v228
	v_xor_b32_e32 v231, 64, v230
	s_mov_b32 m0, s6
	s_nop 0
	global_load_lds_dwordx4 v220, s[2:3]
	s_add_u32 m0, s6, 0x1000
	s_nop 0
	global_load_lds_dwordx4 v221, s[2:3]
	s_add_u32 m0, s6, 0x2000
	s_nop 0
	global_load_lds_dwordx4 v222, s[2:3]
	s_add_u32 m0, s6, 0x3000
	s_nop 0
	global_load_lds_dwordx4 v223, s[2:3]
	s_add_u32 m0, s6, 0x4000
	s_nop 0
	global_load_lds_dwordx4 v224, s[4:5]
	s_add_u32 m0, s6, 0x5000
	s_nop 0
	global_load_lds_dwordx4 v225, s[4:5]
	s_add_u32 m0, s6, 0x6000
	s_nop 0
	global_load_lds_dwordx4 v226, s[4:5]
	s_add_u32 m0, s6, 0x7000
	s_nop 0
	global_load_lds_dwordx4 v227, s[4:5]
	s_add_u32 s2, s2, 0x80
	s_addc_u32 s3, s3, 0
	s_add_u32 s4, s4, 0x80
	s_addc_u32 s5, s5, 0
	s_waitcnt vmcnt(0)
	s_barrier
	ds_read_b128 v[130:133], v230 offset:16384
	ds_read_b128 v[134:137], v230 offset:18432
	ds_read_b128 v[138:141], v230 offset:20480
	ds_read_b128 v[142:145], v230 offset:22528
	ds_read_b128 v[208:211], v228
	ds_read_b128 v[212:215], v228 offset:2048
	s_add_u32 m0, s6, 0x8000
	s_waitcnt lgkmcnt(1)
	v_mfma_f32_16x16x32_bf16 v[126:129], v[130:133], v[208:211], 0
	v_mfma_f32_16x16x32_bf16 v[122:125], v[134:137], v[208:211], 0
	v_mfma_f32_16x16x32_bf16 v[118:121], v[138:141], v[208:211], 0
	v_mfma_f32_16x16x32_bf16 v[114:117], v[142:145], v[208:211], 0
	ds_read_b128 v[216:219], v228 offset:4096
	ds_read_b128 v[146:149], v231 offset:16384
	ds_read_b128 v[150:153], v231 offset:18432
	ds_read_b128 v[154:157], v231 offset:20480
	ds_read_b128 v[158:161], v231 offset:22528
	global_load_lds_dwordx4 v220, s[2:3]
	s_add_u32 m0, s6, 0x9000
	s_waitcnt lgkmcnt(5)
	v_mfma_f32_16x16x32_bf16 v[110:113], v[130:133], v[212:215], 0
	v_mfma_f32_16x16x32_bf16 v[106:109], v[134:137], v[212:215], 0
	v_mfma_f32_16x16x32_bf16 v[102:105], v[138:141], v[212:215], 0
	v_mfma_f32_16x16x32_bf16 v[98:101], v[142:145], v[212:215], 0
	ds_read_b128 v[208:211], v228 offset:6144
	global_load_lds_dwordx4 v221, s[2:3]
	s_add_u32 m0, s6, 0xa000
	s_waitcnt lgkmcnt(5)
	v_mfma_f32_16x16x32_bf16 v[90:93], v[130:133], v[216:219], 0
	v_mfma_f32_16x16x32_bf16 v[82:85], v[134:137], v[216:219], 0
	v_mfma_f32_16x16x32_bf16 v[74:77], v[138:141], v[216:219], 0
	v_mfma_f32_16x16x32_bf16 v[66:69], v[142:145], v[216:219], 0
	ds_read_b128 v[212:215], v229
	global_load_lds_dwordx4 v222, s[2:3]
	s_add_u32 m0, s6, 0xb000
	s_waitcnt lgkmcnt(1)
	v_mfma_f32_16x16x32_bf16 v[58:61], v[130:133], v[208:211], 0
	v_mfma_f32_16x16x32_bf16 v[50:53], v[134:137], v[208:211], 0
	v_mfma_f32_16x16x32_bf16 v[42:45], v[138:141], v[208:211], 0
	v_mfma_f32_16x16x32_bf16 v[34:37], v[142:145], v[208:211], 0
	ds_read_b128 v[216:219], v229 offset:2048
	global_load_lds_dwordx4 v223, s[2:3]
	s_add_u32 m0, s6, 0xc000
	s_waitcnt lgkmcnt(1)
	v_mfma_f32_16x16x32_bf16 v[126:129], v[146:149], v[212:215], v[126:129]
	v_mfma_f32_16x16x32_bf16 v[122:125], v[150:153], v[212:215], v[122:125]
	v_mfma_f32_16x16x32_bf16 v[118:121], v[154:157], v[212:215], v[118:121]
	v_mfma_f32_16x16x32_bf16 v[114:117], v[158:161], v[212:215], v[114:117]
	ds_read_b128 v[208:211], v229 offset:4096
	global_load_lds_dwordx4 v224, s[4:5]
	s_add_u32 m0, s6, 0xd000
	s_waitcnt lgkmcnt(1)
	v_mfma_f32_16x16x32_bf16 v[110:113], v[146:149], v[216:219], v[110:113]
	v_mfma_f32_16x16x32_bf16 v[106:109], v[150:153], v[216:219], v[106:109]
	v_mfma_f32_16x16x32_bf16 v[102:105], v[154:157], v[216:219], v[102:105]
	v_mfma_f32_16x16x32_bf16 v[98:101], v[158:161], v[216:219], v[98:101]
	ds_read_b128 v[212:215], v229 offset:6144
	global_load_lds_dwordx4 v225, s[4:5]
	s_add_u32 m0, s6, 0xe000
	s_waitcnt lgkmcnt(1)
	v_mfma_f32_16x16x32_bf16 v[90:93], v[146:149], v[208:211], v[90:93]
	v_mfma_f32_16x16x32_bf16 v[82:85], v[150:153], v[208:211], v[82:85]
	v_mfma_f32_16x16x32_bf16 v[74:77], v[154:157], v[208:211], v[74:77]
	v_mfma_f32_16x16x32_bf16 v[66:69], v[158:161], v[208:211], v[66:69]
	global_load_lds_dwordx4 v226, s[4:5]
	s_add_u32 m0, s6, 0xf000
	s_waitcnt lgkmcnt(0)
	v_mfma_f32_16x16x32_bf16 v[58:61], v[146:149], v[212:215], v[58:61]
	v_mfma_f32_16x16x32_bf16 v[50:53], v[150:153], v[212:215], v[50:53]
	v_mfma_f32_16x16x32_bf16 v[42:45], v[154:157], v[212:215], v[42:45]
	v_mfma_f32_16x16x32_bf16 v[34:37], v[158:161], v[212:215], v[34:37]
	global_load_lds_dwordx4 v227, s[4:5]
	s_add_u32 s2, s2, 0x80
	s_addc_u32 s3, s3, 0
	s_add_u32 s4, s4, 0x80
	s_addc_u32 s5, s5, 0
	s_waitcnt vmcnt(0) lgkmcnt(0)
	s_barrier
	ds_read_b128 v[130:133], v230 offset:49152
	ds_read_b128 v[134:137], v230 offset:51200
	ds_read_b128 v[138:141], v230 offset:53248
	ds_read_b128 v[142:145], v230 offset:55296
	ds_read_b128 v[208:211], v228 offset:32768
	ds_read_b128 v[212:215], v228 offset:34816
	s_mov_b32 m0, s6
	s_waitcnt lgkmcnt(1)
	v_mfma_f32_16x16x32_bf16 v[126:129], v[130:133], v[208:211], v[126:129]
	v_mfma_f32_16x16x32_bf16 v[122:125], v[134:137], v[208:211], v[122:125]
	v_mfma_f32_16x16x32_bf16 v[118:121], v[138:141], v[208:211], v[118:121]
	v_mfma_f32_16x16x32_bf16 v[114:117], v[142:145], v[208:211], v[114:117]
	ds_read_b128 v[216:219], v228 offset:36864
	ds_read_b128 v[146:149], v231 offset:49152
	ds_read_b128 v[150:153], v231 offset:51200
	ds_read_b128 v[154:157], v231 offset:53248
	ds_read_b128 v[158:161], v231 offset:55296
	global_load_lds_dwordx4 v220, s[2:3]
	s_add_u32 m0, s6, 0x1000
	s_waitcnt lgkmcnt(5)
	v_mfma_f32_16x16x32_bf16 v[110:113], v[130:133], v[212:215], v[110:113]
	v_mfma_f32_16x16x32_bf16 v[106:109], v[134:137], v[212:215], v[106:109]
	v_mfma_f32_16x16x32_bf16 v[102:105], v[138:141], v[212:215], v[102:105]
	v_mfma_f32_16x16x32_bf16 v[98:101], v[142:145], v[212:215], v[98:101]
	ds_read_b128 v[208:211], v228 offset:38912
	global_load_lds_dwordx4 v221, s[2:3]
	s_add_u32 m0, s6, 0x2000
	s_waitcnt lgkmcnt(5)
	v_mfma_f32_16x16x32_bf16 v[90:93], v[130:133], v[216:219], v[90:93]
	v_mfma_f32_16x16x32_bf16 v[82:85], v[134:137], v[216:219], v[82:85]
	v_mfma_f32_16x16x32_bf16 v[74:77], v[138:141], v[216:219], v[74:77]
	v_mfma_f32_16x16x32_bf16 v[66:69], v[142:145], v[216:219], v[66:69]
	ds_read_b128 v[212:215], v229 offset:32768
	global_load_lds_dwordx4 v222, s[2:3]
	s_add_u32 m0, s6, 0x3000
	s_waitcnt lgkmcnt(1)
	v_mfma_f32_16x16x32_bf16 v[58:61], v[130:133], v[208:211], v[58:61]
	v_mfma_f32_16x16x32_bf16 v[50:53], v[134:137], v[208:211], v[50:53]
	v_mfma_f32_16x16x32_bf16 v[42:45], v[138:141], v[208:211], v[42:45]
	v_mfma_f32_16x16x32_bf16 v[34:37], v[142:145], v[208:211], v[34:37]
	ds_read_b128 v[216:219], v229 offset:34816
	global_load_lds_dwordx4 v223, s[2:3]
	s_add_u32 m0, s6, 0x4000
	s_waitcnt lgkmcnt(1)
	v_mfma_f32_16x16x32_bf16 v[126:129], v[146:149], v[212:215], v[126:129]
	v_mfma_f32_16x16x32_bf16 v[122:125], v[150:153], v[212:215], v[122:125]
	v_mfma_f32_16x16x32_bf16 v[118:121], v[154:157], v[212:215], v[118:121]
	v_mfma_f32_16x16x32_bf16 v[114:117], v[158:161], v[212:215], v[114:117]
	ds_read_b128 v[208:211], v229 offset:36864
	global_load_lds_dwordx4 v224, s[4:5]
	s_add_u32 m0, s6, 0x5000
	s_waitcnt lgkmcnt(1)
	v_mfma_f32_16x16x32_bf16 v[110:113], v[146:149], v[216:219], v[110:113]
	v_mfma_f32_16x16x32_bf16 v[106:109], v[150:153], v[216:219], v[106:109]
	v_mfma_f32_16x16x32_bf16 v[102:105], v[154:157], v[216:219], v[102:105]
	v_mfma_f32_16x16x32_bf16 v[98:101], v[158:161], v[216:219], v[98:101]
	ds_read_b128 v[212:215], v229 offset:38912
	global_load_lds_dwordx4 v225, s[4:5]
	s_add_u32 m0, s6, 0x6000
	s_waitcnt lgkmcnt(1)
	v_mfma_f32_16x16x32_bf16 v[90:93], v[146:149], v[208:211], v[90:93]
	v_mfma_f32_16x16x32_bf16 v[82:85], v[150:153], v[208:211], v[82:85]
	v_mfma_f32_16x16x32_bf16 v[74:77], v[154:157], v[208:211], v[74:77]
	v_mfma_f32_16x16x32_bf16 v[66:69], v[158:161], v[208:211], v[66:69]
	global_load_lds_dwordx4 v226, s[4:5]
	s_add_u32 m0, s6, 0x7000
	s_waitcnt lgkmcnt(0)
	v_mfma_f32_16x16x32_bf16 v[58:61], v[146:149], v[212:215], v[58:61]
	v_mfma_f32_16x16x32_bf16 v[50:53], v[150:153], v[212:215], v[50:53]
	v_mfma_f32_16x16x32_bf16 v[42:45], v[154:157], v[212:215], v[42:45]
	v_mfma_f32_16x16x32_bf16 v[34:37], v[158:161], v[212:215], v[34:37]
	global_load_lds_dwordx4 v227, s[4:5]
	s_add_u32 s2, s2, 0x80
	s_addc_u32 s3, s3, 0
	s_add_u32 s4, s4, 0x80
	s_addc_u32 s5, s5, 0
	s_waitcnt vmcnt(0) lgkmcnt(0)
	s_barrier
	s_movk_i32 s7, 2
.Lm2_loop:
	ds_read_b128 v[130:133], v230 offset:16384
	ds_read_b128 v[134:137], v230 offset:18432
	ds_read_b128 v[138:141], v230 offset:20480
	ds_read_b128 v[142:145], v230 offset:22528
	ds_read_b128 v[208:211], v228
	ds_read_b128 v[212:215], v228 offset:2048
	s_add_u32 m0, s6, 0x8000
	s_waitcnt lgkmcnt(1)
	v_mfma_f32_16x16x32_bf16 v[126:129], v[130:133], v[208:211], v[126:129]
	v_mfma_f32_16x16x32_bf16 v[122:125], v[134:137], v[208:211], v[122:125]
	v_mfma_f32_16x16x32_bf16 v[118:121], v[138:141], v[208:211], v[118:121]
	v_mfma_f32_16x16x32_bf16 v[114:117], v[142:145], v[208:211], v[114:117]
	ds_read_b128 v[216:219], v228 offset:4096
	ds_read_b128 v[146:149], v231 offset:16384
	ds_read_b128 v[150:153], v231 offset:18432
	ds_read_b128 v[154:157], v231 offset:20480
	ds_read_b128 v[158:161], v231 offset:22528
	global_load_lds_dwordx4 v220, s[2:3]
	s_add_u32 m0, s6, 0x9000
	s_waitcnt lgkmcnt(5)
	v_mfma_f32_16x16x32_bf16 v[110:113], v[130:133], v[212:215], v[110:113]
	v_mfma_f32_16x16x32_bf16 v[106:109], v[134:137], v[212:215], v[106:109]
	v_mfma_f32_16x16x32_bf16 v[102:105], v[138:141], v[212:215], v[102:105]
	v_mfma_f32_16x16x32_bf16 v[98:101], v[142:145], v[212:215], v[98:101]
	ds_read_b128 v[208:211], v228 offset:6144
	global_load_lds_dwordx4 v221, s[2:3]
	s_add_u32 m0, s6, 0xa000
	s_waitcnt lgkmcnt(5)
	v_mfma_f32_16x16x32_bf16 v[90:93], v[130:133], v[216:219], v[90:93]
	v_mfma_f32_16x16x32_bf16 v[82:85], v[134:137], v[216:219], v[82:85]
	v_mfma_f32_16x16x32_bf16 v[74:77], v[138:141], v[216:219], v[74:77]
	v_mfma_f32_16x16x32_bf16 v[66:69], v[142:145], v[216:219], v[66:69]
	ds_read_b128 v[212:215], v229
	global_load_lds_dwordx4 v222, s[2:3]
	s_add_u32 m0, s6, 0xb000
	s_waitcnt lgkmcnt(1)
	v_mfma_f32_16x16x32_bf16 v[58:61], v[130:133], v[208:211], v[58:61]
	v_mfma_f32_16x16x32_bf16 v[50:53], v[134:137], v[208:211], v[50:53]
	v_mfma_f32_16x16x32_bf16 v[42:45], v[138:141], v[208:211], v[42:45]
	v_mfma_f32_16x16x32_bf16 v[34:37], v[142:145], v[208:211], v[34:37]
	ds_read_b128 v[216:219], v229 offset:2048
	global_load_lds_dwordx4 v223, s[2:3]
	s_add_u32 m0, s6, 0xc000
	s_waitcnt lgkmcnt(1)
	v_mfma_f32_16x16x32_bf16 v[126:129], v[146:149], v[212:215], v[126:129]
	v_mfma_f32_16x16x32_bf16 v[122:125], v[150:153], v[212:215], v[122:125]
	v_mfma_f32_16x16x32_bf16 v[118:121], v[154:157], v[212:215], v[118:121]
	v_mfma_f32_16x16x32_bf16 v[114:117], v[158:161], v[212:215], v[114:117]
	ds_read_b128 v[208:211], v229 offset:4096
	global_load_lds_dwordx4 v224, s[4:5]
	s_add_u32 m0, s6, 0xd000
	s_waitcnt lgkmcnt(1)
	v_mfma_f32_16x16x32_bf16 v[110:113], v[146:149], v[216:219], v[110:113]
	v_mfma_f32_16x16x32_bf16 v[106:109], v[150:153], v[216:219], v[106:109]
	v_mfma_f32_16x16x32_bf16 v[102:105], v[154:157], v[216:219], v[102:105]
	v_mfma_f32_16x16x32_bf16 v[98:101], v[158:161], v[216:219], v[98:101]
	ds_read_b128 v[212:215], v229 offset:6144
	global_load_lds_dwordx4 v225, s[4:5]
	s_add_u32 m0, s6, 0xe000
	s_waitcnt lgkmcnt(1)
	v_mfma_f32_16x16x32_bf16 v[90:93], v[146:149], v[208:211], v[90:93]
	v_mfma_f32_16x16x32_bf16 v[82:85], v[150:153], v[208:211], v[82:85]
	v_mfma_f32_16x16x32_bf16 v[74:77], v[154:157], v[208:211], v[74:77]
	v_mfma_f32_16x16x32_bf16 v[66:69], v[158:161], v[208:211], v[66:69]
	global_load_lds_dwordx4 v226, s[4:5]
	s_add_u32 m0, s6, 0xf000
	s_waitcnt lgkmcnt(0)
	v_mfma_f32_16x16x32_bf16 v[58:61], v[146:149], v[212:215], v[58:61]
	v_mfma_f32_16x16x32_bf16 v[50:53], v[150:153], v[212:215], v[50:53]
	v_mfma_f32_16x16x32_bf16 v[42:45], v[154:157], v[212:215], v[42:45]
	v_mfma_f32_16x16x32_bf16 v[34:37], v[158:161], v[212:215], v[34:37]
	global_load_lds_dwordx4 v227, s[4:5]
	s_add_u32 s2, s2, 0x80
	s_addc_u32 s3, s3, 0
	s_add_u32 s4, s4, 0x80
	s_addc_u32 s5, s5, 0
	s_waitcnt vmcnt(0) lgkmcnt(0)
	s_barrier
	ds_read_b128 v[130:133], v230 offset:49152
	ds_read_b128 v[134:137], v230 offset:51200
	ds_read_b128 v[138:141], v230 offset:53248
	ds_read_b128 v[142:145], v230 offset:55296
	ds_read_b128 v[208:211], v228 offset:32768
	ds_read_b128 v[212:215], v228 offset:34816
	s_mov_b32 m0, s6
	s_waitcnt lgkmcnt(1)
	v_mfma_f32_16x16x32_bf16 v[126:129], v[130:133], v[208:211], v[126:129]
	v_mfma_f32_16x16x32_bf16 v[122:125], v[134:137], v[208:211], v[122:125]
	v_mfma_f32_16x16x32_bf16 v[118:121], v[138:141], v[208:211], v[118:121]
	v_mfma_f32_16x16x32_bf16 v[114:117], v[142:145], v[208:211], v[114:117]
	ds_read_b128 v[216:219], v228 offset:36864
	ds_read_b128 v[146:149], v231 offset:49152
	ds_read_b128 v[150:153], v231 offset:51200
	ds_read_b128 v[154:157], v231 offset:53248
	ds_read_b128 v[158:161], v231 offset:55296
	global_load_lds_dwordx4 v220, s[2:3]
	s_add_u32 m0, s6, 0x1000
	s_waitcnt lgkmcnt(5)
	v_mfma_f32_16x16x32_bf16 v[110:113], v[130:133], v[212:215], v[110:113]
	v_mfma_f32_16x16x32_bf16 v[106:109], v[134:137], v[212:215], v[106:109]
	v_mfma_f32_16x16x32_bf16 v[102:105], v[138:141], v[212:215], v[102:105]
	v_mfma_f32_16x16x32_bf16 v[98:101], v[142:145], v[212:215], v[98:101]
	ds_read_b128 v[208:211], v228 offset:38912
	global_load_lds_dwordx4 v221, s[2:3]
	s_add_u32 m0, s6, 0x2000
	s_waitcnt lgkmcnt(5)
	v_mfma_f32_16x16x32_bf16 v[90:93], v[130:133], v[216:219], v[90:93]
	v_mfma_f32_16x16x32_bf16 v[82:85], v[134:137], v[216:219], v[82:85]
	v_mfma_f32_16x16x32_bf16 v[74:77], v[138:141], v[216:219], v[74:77]
	v_mfma_f32_16x16x32_bf16 v[66:69], v[142:145], v[216:219], v[66:69]
	ds_read_b128 v[212:215], v229 offset:32768
	global_load_lds_dwordx4 v222, s[2:3]
	s_add_u32 m0, s6, 0x3000
	s_waitcnt lgkmcnt(1)
	v_mfma_f32_16x16x32_bf16 v[58:61], v[130:133], v[208:211], v[58:61]
	v_mfma_f32_16x16x32_bf16 v[50:53], v[134:137], v[208:211], v[50:53]
	v_mfma_f32_16x16x32_bf16 v[42:45], v[138:141], v[208:211], v[42:45]
	v_mfma_f32_16x16x32_bf16 v[34:37], v[142:145], v[208:211], v[34:37]
	ds_read_b128 v[216:219], v229 offset:34816
	global_load_lds_dwordx4 v223, s[2:3]
	s_add_u32 m0, s6, 0x4000
	s_waitcnt lgkmcnt(1)
	v_mfma_f32_16x16x32_bf16 v[126:129], v[146:149], v[212:215], v[126:129]
	v_mfma_f32_16x16x32_bf16 v[122:125], v[150:153], v[212:215], v[122:125]
	v_mfma_f32_16x16x32_bf16 v[118:121], v[154:157], v[212:215], v[118:121]
	v_mfma_f32_16x16x32_bf16 v[114:117], v[158:161], v[212:215], v[114:117]
	ds_read_b128 v[208:211], v229 offset:36864
	global_load_lds_dwordx4 v224, s[4:5]
	s_add_u32 m0, s6, 0x5000
	s_waitcnt lgkmcnt(1)
	v_mfma_f32_16x16x32_bf16 v[110:113], v[146:149], v[216:219], v[110:113]
	v_mfma_f32_16x16x32_bf16 v[106:109], v[150:153], v[216:219], v[106:109]
	v_mfma_f32_16x16x32_bf16 v[102:105], v[154:157], v[216:219], v[102:105]
	v_mfma_f32_16x16x32_bf16 v[98:101], v[158:161], v[216:219], v[98:101]
	ds_read_b128 v[212:215], v229 offset:38912
	global_load_lds_dwordx4 v225, s[4:5]
	s_add_u32 m0, s6, 0x6000
	s_waitcnt lgkmcnt(1)
	v_mfma_f32_16x16x32_bf16 v[90:93], v[146:149], v[208:211], v[90:93]
	v_mfma_f32_16x16x32_bf16 v[82:85], v[150:153], v[208:211], v[82:85]
	v_mfma_f32_16x16x32_bf16 v[74:77], v[154:157], v[208:211], v[74:77]
	v_mfma_f32_16x16x32_bf16 v[66:69], v[158:161], v[208:211], v[66:69]
	global_load_lds_dwordx4 v226, s[4:5]
	s_add_u32 m0, s6, 0x7000
	s_waitcnt lgkmcnt(0)
	v_mfma_f32_16x16x32_bf16 v[58:61], v[146:149], v[212:215], v[58:61]
	v_mfma_f32_16x16x32_bf16 v[50:53], v[150:153], v[212:215], v[50:53]
	v_mfma_f32_16x16x32_bf16 v[42:45], v[154:157], v[212:215], v[42:45]
	v_mfma_f32_16x16x32_bf16 v[34:37], v[158:161], v[212:215], v[34:37]
	global_load_lds_dwordx4 v227, s[4:5]
	s_add_u32 s2, s2, 0x80
	s_addc_u32 s3, s3, 0
	s_add_u32 s4, s4, 0x80
	s_addc_u32 s5, s5, 0
	s_add_i32 s7, s7, -1
	s_waitcnt vmcnt(0) lgkmcnt(0)
	s_barrier
	s_cmp_lg_u32 s7, 0
	s_cbranch_scc1 .Lm2_loop
	ds_read_b128 v[130:133], v230 offset:16384
	ds_read_b128 v[134:137], v230 offset:18432
	ds_read_b128 v[138:141], v230 offset:20480
	ds_read_b128 v[142:145], v230 offset:22528
	ds_read_b128 v[208:211], v228
	ds_read_b128 v[212:215], v228 offset:2048
	s_add_u32 m0, s6, 0x8000
	s_waitcnt lgkmcnt(1)
	v_mfma_f32_16x16x32_bf16 v[126:129], v[130:133], v[208:211], v[126:129]
	v_mfma_f32_16x16x32_bf16 v[122:125], v[134:137], v[208:211], v[122:125]
	v_mfma_f32_16x16x32_bf16 v[118:121], v[138:141], v[208:211], v[118:121]
	v_mfma_f32_16x16x32_bf16 v[114:117], v[142:145], v[208:211], v[114:117]
	ds_read_b128 v[216:219], v228 offset:4096
	ds_read_b128 v[146:149], v231 offset:16384
	ds_read_b128 v[150:153], v231 offset:18432
	ds_read_b128 v[154:157], v231 offset:20480
	ds_read_b128 v[158:161], v231 offset:22528
	global_load_lds_dwordx4 v220, s[2:3]
	s_add_u32 m0, s6, 0x9000
	s_waitcnt lgkmcnt(5)
	v_mfma_f32_16x16x32_bf16 v[110:113], v[130:133], v[212:215], v[110:113]
	v_mfma_f32_16x16x32_bf16 v[106:109], v[134:137], v[212:215], v[106:109]
	v_mfma_f32_16x16x32_bf16 v[102:105], v[138:141], v[212:215], v[102:105]
	v_mfma_f32_16x16x32_bf16 v[98:101], v[142:145], v[212:215], v[98:101]
	ds_read_b128 v[208:211], v228 offset:6144
	global_load_lds_dwordx4 v221, s[2:3]
	s_add_u32 m0, s6, 0xa000
	s_waitcnt lgkmcnt(5)
	v_mfma_f32_16x16x32_bf16 v[90:93], v[130:133], v[216:219], v[90:93]
	v_mfma_f32_16x16x32_bf16 v[82:85], v[134:137], v[216:219], v[82:85]
	v_mfma_f32_16x16x32_bf16 v[74:77], v[138:141], v[216:219], v[74:77]
	v_mfma_f32_16x16x32_bf16 v[66:69], v[142:145], v[216:219], v[66:69]
	ds_read_b128 v[212:215], v229
	global_load_lds_dwordx4 v222, s[2:3]
	s_add_u32 m0, s6, 0xb000
	s_waitcnt lgkmcnt(1)
	v_mfma_f32_16x16x32_bf16 v[58:61], v[130:133], v[208:211], v[58:61]
	v_mfma_f32_16x16x32_bf16 v[50:53], v[134:137], v[208:211], v[50:53]
	v_mfma_f32_16x16x32_bf16 v[42:45], v[138:141], v[208:211], v[42:45]
	v_mfma_f32_16x16x32_bf16 v[34:37], v[142:145], v[208:211], v[34:37]
	ds_read_b128 v[216:219], v229 offset:2048
	global_load_lds_dwordx4 v223, s[2:3]
	s_add_u32 m0, s6, 0xc000
	s_waitcnt lgkmcnt(1)
	v_mfma_f32_16x16x32_bf16 v[126:129], v[146:149], v[212:215], v[126:129]
	v_mfma_f32_16x16x32_bf16 v[122:125], v[150:153], v[212:215], v[122:125]
	v_mfma_f32_16x16x32_bf16 v[118:121], v[154:157], v[212:215], v[118:121]
	v_mfma_f32_16x16x32_bf16 v[114:117], v[158:161], v[212:215], v[114:117]
	ds_read_b128 v[208:211], v229 offset:4096
	global_load_lds_dwordx4 v224, s[4:5]
	s_add_u32 m0, s6, 0xd000
	s_waitcnt lgkmcnt(1)
	v_mfma_f32_16x16x32_bf16 v[110:113], v[146:149], v[216:219], v[110:113]
	v_mfma_f32_16x16x32_bf16 v[106:109], v[150:153], v[216:219], v[106:109]
	v_mfma_f32_16x16x32_bf16 v[102:105], v[154:157], v[216:219], v[102:105]
	v_mfma_f32_16x16x32_bf16 v[98:101], v[158:161], v[216:219], v[98:101]
	ds_read_b128 v[212:215], v229 offset:6144
	global_load_lds_dwordx4 v225, s[4:5]
	s_add_u32 m0, s6, 0xe000
	s_waitcnt lgkmcnt(1)
	v_mfma_f32_16x16x32_bf16 v[90:93], v[146:149], v[208:211], v[90:93]
	v_mfma_f32_16x16x32_bf16 v[82:85], v[150:153], v[208:211], v[82:85]
	v_mfma_f32_16x16x32_bf16 v[74:77], v[154:157], v[208:211], v[74:77]
	v_mfma_f32_16x16x32_bf16 v[66:69], v[158:161], v[208:211], v[66:69]
	global_load_lds_dwordx4 v226, s[4:5]
	s_add_u32 m0, s6, 0xf000
	s_waitcnt lgkmcnt(0)
	v_mfma_f32_16x16x32_bf16 v[58:61], v[146:149], v[212:215], v[58:61]
	v_mfma_f32_16x16x32_bf16 v[50:53], v[150:153], v[212:215], v[50:53]
	v_mfma_f32_16x16x32_bf16 v[42:45], v[154:157], v[212:215], v[42:45]
	v_mfma_f32_16x16x32_bf16 v[34:37], v[158:161], v[212:215], v[34:37]
	global_load_lds_dwordx4 v227, s[4:5]
	s_add_u32 s2, s2, 0x80
	s_addc_u32 s3, s3, 0
	s_add_u32 s4, s4, 0x80
	s_addc_u32 s5, s5, 0
	s_waitcnt vmcnt(0) lgkmcnt(0)
	s_barrier
	ds_read_b128 v[130:133], v230 offset:49152
	ds_read_b128 v[134:137], v230 offset:51200
	ds_read_b128 v[138:141], v230 offset:53248
	ds_read_b128 v[142:145], v230 offset:55296
	ds_read_b128 v[208:211], v228 offset:32768
	ds_read_b128 v[212:215], v228 offset:34816
	s_waitcnt lgkmcnt(1)
	v_mfma_f32_16x16x32_bf16 v[126:129], v[130:133], v[208:211], v[126:129]
	v_mfma_f32_16x16x32_bf16 v[122:125], v[134:137], v[208:211], v[122:125]
	v_mfma_f32_16x16x32_bf16 v[118:121], v[138:141], v[208:211], v[118:121]
	v_mfma_f32_16x16x32_bf16 v[114:117], v[142:145], v[208:211], v[114:117]
	ds_read_b128 v[216:219], v228 offset:36864
	ds_read_b128 v[146:149], v231 offset:49152
	ds_read_b128 v[150:153], v231 offset:51200
	ds_read_b128 v[154:157], v231 offset:53248
	ds_read_b128 v[158:161], v231 offset:55296
	s_waitcnt lgkmcnt(5)
	v_mfma_f32_16x16x32_bf16 v[110:113], v[130:133], v[212:215], v[110:113]
	v_mfma_f32_16x16x32_bf16 v[106:109], v[134:137], v[212:215], v[106:109]
	v_mfma_f32_16x16x32_bf16 v[102:105], v[138:141], v[212:215], v[102:105]
	v_mfma_f32_16x16x32_bf16 v[98:101], v[142:145], v[212:215], v[98:101]
	ds_read_b128 v[208:211], v228 offset:38912
	s_waitcnt lgkmcnt(5)
	v_mfma_f32_16x16x32_bf16 v[90:93], v[130:133], v[216:219], v[90:93]
	v_mfma_f32_16x16x32_bf16 v[82:85], v[134:137], v[216:219], v[82:85]
	v_mfma_f32_16x16x32_bf16 v[74:77], v[138:141], v[216:219], v[74:77]
	v_mfma_f32_16x16x32_bf16 v[66:69], v[142:145], v[216:219], v[66:69]
	ds_read_b128 v[212:215], v229 offset:32768
	s_waitcnt lgkmcnt(1)
	v_mfma_f32_16x16x32_bf16 v[58:61], v[130:133], v[208:211], v[58:61]
	v_mfma_f32_16x16x32_bf16 v[50:53], v[134:137], v[208:211], v[50:53]
	v_mfma_f32_16x16x32_bf16 v[42:45], v[138:141], v[208:211], v[42:45]
	v_mfma_f32_16x16x32_bf16 v[34:37], v[142:145], v[208:211], v[34:37]
	ds_read_b128 v[216:219], v229 offset:34816
	s_waitcnt lgkmcnt(1)
	v_mfma_f32_16x16x32_bf16 v[126:129], v[146:149], v[212:215], v[126:129]
	v_mfma_f32_16x16x32_bf16 v[122:125], v[150:153], v[212:215], v[122:125]
	v_mfma_f32_16x16x32_bf16 v[118:121], v[154:157], v[212:215], v[118:121]
	v_mfma_f32_16x16x32_bf16 v[114:117], v[158:161], v[212:215], v[114:117]
	ds_read_b128 v[208:211], v229 offset:36864
	s_waitcnt lgkmcnt(1)
	v_mfma_f32_16x16x32_bf16 v[110:113], v[146:149], v[216:219], v[110:113]
	v_mfma_f32_16x16x32_bf16 v[106:109], v[150:153], v[216:219], v[106:109]
	v_mfma_f32_16x16x32_bf16 v[102:105], v[154:157], v[216:219], v[102:105]
	v_mfma_f32_16x16x32_bf16 v[98:101], v[158:161], v[216:219], v[98:101]
	ds_read_b128 v[212:215], v229 offset:38912
	s_waitcnt lgkmcnt(1)
	v_mfma_f32_16x16x32_bf16 v[90:93], v[146:149], v[208:211], v[90:93]
	v_mfma_f32_16x16x32_bf16 v[82:85], v[150:153], v[208:211], v[82:85]
	v_mfma_f32_16x16x32_bf16 v[74:77], v[154:157], v[208:211], v[74:77]
	v_mfma_f32_16x16x32_bf16 v[66:69], v[158:161], v[208:211], v[66:69]
	s_waitcnt lgkmcnt(0)
	v_mfma_f32_16x16x32_bf16 v[58:61], v[146:149], v[212:215], v[58:61]
	v_mfma_f32_16x16x32_bf16 v[50:53], v[150:153], v[212:215], v[50:53]
	v_mfma_f32_16x16x32_bf16 v[42:45], v[154:157], v[212:215], v[42:45]
	v_mfma_f32_16x16x32_bf16 v[34:37], v[158:161], v[212:215], v[34:37]
	s_waitcnt lgkmcnt(0)
	s_barrier
	s_nop 7
	s_nop 2
	s_movk_i32 s92, 0x480

.LBB0_112:
	s_cmp_eq_u32 s5, 1
	s_cselect_b32 s3, s85, s87
	s_cselect_b32 s2, s84, s86
	s_cselect_b32 s7, s51, s53
	s_cselect_b32 s6, s50, s52
	v_mov_b32_e32 v2, v163
	v_lshl_add_u64 v[4:5], s[2:3], 0, v[182:183]
	v_lshl_add_u64 v[6:7], s[6:7], 0, v[186:187]
	s_movk_i32 s6, 0x480
	v_ashrrev_i32_e32 v3, 3, v2
	v_lshlrev_b32_e32 v0, 4, v2
	v_mad_i64_i32 v[4:5], s[2:3], v3, s6, v[4:5]
	v_and_b32_e32 v0, 0x70, v0
	v_lshl_add_u64 v[132:133], v[4:5], 0, v[0:1]
	v_mad_i64_i32 v[4:5], s[2:3], v3, s6, v[6:7]
	s_mov_b32 s2, 0x9000
	v_lshl_add_u64 v[134:135], v[4:5], 0, v[0:1]
	v_and_b32_e32 v82, 7, v163
	v_bfe_u32 v83, v163, 4, 3
	v_xor_b32_e32 v83, v83, v82
	v_sub_u32_e32 v83, v83, v82
	v_lshlrev_b32_e32 v83, 4, v83
	v_lshrrev_b32_e32 v84, 6, v163
	v_lshlrev_b32_e32 v84, 10, v84
	v_readfirstlane_b32 s2, v132
	v_readfirstlane_b32 s3, v133
	v_readfirstlane_b32 s6, v134
	v_readfirstlane_b32 s7, v135
	v_readfirstlane_b32 s8, v84
	s_nop 3
	v_subrev_u32_e32 v154, s2, v132
	v_subrev_u32_e32 v158, s6, v134
	v_add_u32_e32 v154, v154, v83
	v_add_u32_e32 v158, v158, v83
	v_add_u32_e32 v155, 0x9000, v154
	v_add_u32_e32 v159, 0x9000, v158
	v_add_u32_e32 v156, 0x12000, v154
	v_add_u32_e32 v160, 0x12000, v158
	v_add_u32_e32 v157, 0x1b000, v154
	v_add_u32_e32 v161, 0x1b000, v158
	v_lshlrev_b32_e32 v82, 3, v163
	v_lshlrev_b32_e32 v83, 7, v163
	v_and_b32_e32 v84, 0x2000, v83
	v_and_b32_e32 v83, 0x780, v83
	v_and_b32_e32 v189, 64, v82
	v_xor_b32_e32 v82, v82, v163
	v_and_b32_e32 v82, 48, v82
	v_or3_b32 v82, v83, v189, v82
	v_lshlrev_b32_e32 v83, 6, v163
	v_and_b32_e32 v83, 0xffffe000, v83
	v_or_b32_e32 v190, v82, v84
	v_or_b32_e32 v188, v82, v83
	v_xor_b32_e32 v189, 64, v188
	v_xor_b32_e32 v191, 64, v190
	s_mov_b32 m0, s8
	s_nop 0
	global_load_lds_dwordx4 v154, s[2:3]
	s_add_u32 m0, s8, 0x1000
	s_nop 0
	global_load_lds_dwordx4 v155, s[2:3]
	s_add_u32 m0, s8, 0x2000
	s_nop 0
	global_load_lds_dwordx4 v156, s[2:3]
	s_add_u32 m0, s8, 0x3000
	s_nop 0
	global_load_lds_dwordx4 v157, s[2:3]
	s_add_u32 m0, s8, 0x4000
	s_nop 0
	global_load_lds_dwordx4 v158, s[6:7]
	s_add_u32 m0, s8, 0x5000
	s_nop 0
	global_load_lds_dwordx4 v159, s[6:7]
	s_add_u32 m0, s8, 0x6000
	s_nop 0
	global_load_lds_dwordx4 v160, s[6:7]
	s_add_u32 m0, s8, 0x7000
	s_nop 0
	global_load_lds_dwordx4 v161, s[6:7]
	s_add_u32 s2, s2, 0x80
	s_addc_u32 s3, s3, 0
	s_add_u32 s6, s6, 0x80
	s_addc_u32 s7, s7, 0
	s_waitcnt vmcnt(0)
	s_barrier
	ds_read_b128 v[66:69], v190 offset:16384
	ds_read_b128 v[70:73], v190 offset:18432
	ds_read_b128 v[74:77], v190 offset:20480
	ds_read_b128 v[78:81], v190 offset:22528
	ds_read_b128 v[142:145], v188
	ds_read_b128 v[146:149], v188 offset:2048
	s_add_u32 m0, s8, 0x8000
	s_waitcnt lgkmcnt(1)
	v_mfma_f32_16x16x32_bf16 v[62:65], v[66:69], v[142:145], 0
	v_mfma_f32_16x16x32_bf16 v[58:61], v[70:73], v[142:145], 0
	v_mfma_f32_16x16x32_bf16 v[54:57], v[74:77], v[142:145], 0
	v_mfma_f32_16x16x32_bf16 v[50:53], v[78:81], v[142:145], 0
	ds_read_b128 v[150:153], v188 offset:4096
	ds_read_b128 v[82:85], v191 offset:16384
	ds_read_b128 v[86:89], v191 offset:18432
	ds_read_b128 v[90:93], v191 offset:20480
	ds_read_b128 v[94:97], v191 offset:22528
	global_load_lds_dwordx4 v154, s[2:3]
	s_add_u32 m0, s8, 0x9000
	s_waitcnt lgkmcnt(5)
	v_mfma_f32_16x16x32_bf16 v[46:49], v[66:69], v[146:149], 0
	v_mfma_f32_16x16x32_bf16 v[42:45], v[70:73], v[146:149], 0
	v_mfma_f32_16x16x32_bf16 v[38:41], v[74:77], v[146:149], 0
	v_mfma_f32_16x16x32_bf16 v[34:37], v[78:81], v[146:149], 0
	ds_read_b128 v[142:145], v188 offset:6144
	global_load_lds_dwordx4 v155, s[2:3]
	s_add_u32 m0, s8, 0xa000
	s_waitcnt lgkmcnt(5)
	v_mfma_f32_16x16x32_bf16 v[30:33], v[66:69], v[150:153], 0
	v_mfma_f32_16x16x32_bf16 v[26:29], v[70:73], v[150:153], 0
	v_mfma_f32_16x16x32_bf16 v[22:25], v[74:77], v[150:153], 0
	v_mfma_f32_16x16x32_bf16 v[18:21], v[78:81], v[150:153], 0
	ds_read_b128 v[146:149], v189
	global_load_lds_dwordx4 v156, s[2:3]
	s_add_u32 m0, s8, 0xb000
	s_waitcnt lgkmcnt(1)
	v_mfma_f32_16x16x32_bf16 v[14:17], v[66:69], v[142:145], 0
	v_mfma_f32_16x16x32_bf16 v[10:13], v[70:73], v[142:145], 0
	v_mfma_f32_16x16x32_bf16 v[6:9], v[74:77], v[142:145], 0
	v_mfma_f32_16x16x32_bf16 v[2:5], v[78:81], v[142:145], 0
	ds_read_b128 v[150:153], v189 offset:2048
	global_load_lds_dwordx4 v157, s[2:3]
	s_add_u32 m0, s8, 0xc000
	s_waitcnt lgkmcnt(1)
	v_mfma_f32_16x16x32_bf16 v[62:65], v[82:85], v[146:149], v[62:65]
	v_mfma_f32_16x16x32_bf16 v[58:61], v[86:89], v[146:149], v[58:61]
	v_mfma_f32_16x16x32_bf16 v[54:57], v[90:93], v[146:149], v[54:57]
	v_mfma_f32_16x16x32_bf16 v[50:53], v[94:97], v[146:149], v[50:53]
	ds_read_b128 v[142:145], v189 offset:4096
	global_load_lds_dwordx4 v158, s[6:7]
	s_add_u32 m0, s8, 0xd000
	s_waitcnt lgkmcnt(1)
	v_mfma_f32_16x16x32_bf16 v[46:49], v[82:85], v[150:153], v[46:49]
	v_mfma_f32_16x16x32_bf16 v[42:45], v[86:89], v[150:153], v[42:45]
	v_mfma_f32_16x16x32_bf16 v[38:41], v[90:93], v[150:153], v[38:41]
	v_mfma_f32_16x16x32_bf16 v[34:37], v[94:97], v[150:153], v[34:37]
	ds_read_b128 v[146:149], v189 offset:6144
	global_load_lds_dwordx4 v159, s[6:7]
	s_add_u32 m0, s8, 0xe000
	s_waitcnt lgkmcnt(1)
	v_mfma_f32_16x16x32_bf16 v[30:33], v[82:85], v[142:145], v[30:33]
	v_mfma_f32_16x16x32_bf16 v[26:29], v[86:89], v[142:145], v[26:29]
	v_mfma_f32_16x16x32_bf16 v[22:25], v[90:93], v[142:145], v[22:25]
	v_mfma_f32_16x16x32_bf16 v[18:21], v[94:97], v[142:145], v[18:21]
	global_load_lds_dwordx4 v160, s[6:7]
	s_add_u32 m0, s8, 0xf000
	s_waitcnt lgkmcnt(0)
	v_mfma_f32_16x16x32_bf16 v[14:17], v[82:85], v[146:149], v[14:17]
	v_mfma_f32_16x16x32_bf16 v[10:13], v[86:89], v[146:149], v[10:13]
	v_mfma_f32_16x16x32_bf16 v[6:9], v[90:93], v[146:149], v[6:9]
	v_mfma_f32_16x16x32_bf16 v[2:5], v[94:97], v[146:149], v[2:5]
	global_load_lds_dwordx4 v161, s[6:7]
	s_add_u32 s2, s2, 0x80
	s_addc_u32 s3, s3, 0
	s_add_u32 s6, s6, 0x80
	s_addc_u32 s7, s7, 0
	s_waitcnt vmcnt(0) lgkmcnt(0)
	s_barrier
	ds_read_b128 v[66:69], v190 offset:49152
	ds_read_b128 v[70:73], v190 offset:51200
	ds_read_b128 v[74:77], v190 offset:53248
	ds_read_b128 v[78:81], v190 offset:55296
	ds_read_b128 v[142:145], v188 offset:32768
	ds_read_b128 v[146:149], v188 offset:34816
	s_mov_b32 m0, s8
	s_waitcnt lgkmcnt(1)
	v_mfma_f32_16x16x32_bf16 v[62:65], v[66:69], v[142:145], v[62:65]
	v_mfma_f32_16x16x32_bf16 v[58:61], v[70:73], v[142:145], v[58:61]
	v_mfma_f32_16x16x32_bf16 v[54:57], v[74:77], v[142:145], v[54:57]
	v_mfma_f32_16x16x32_bf16 v[50:53], v[78:81], v[142:145], v[50:53]
	ds_read_b128 v[150:153], v188 offset:36864
	ds_read_b128 v[82:85], v191 offset:49152
	ds_read_b128 v[86:89], v191 offset:51200
	ds_read_b128 v[90:93], v191 offset:53248
	ds_read_b128 v[94:97], v191 offset:55296
	global_load_lds_dwordx4 v154, s[2:3]
	s_add_u32 m0, s8, 0x1000
	s_waitcnt lgkmcnt(5)
	v_mfma_f32_16x16x32_bf16 v[46:49], v[66:69], v[146:149], v[46:49]
	v_mfma_f32_16x16x32_bf16 v[42:45], v[70:73], v[146:149], v[42:45]
	v_mfma_f32_16x16x32_bf16 v[38:41], v[74:77], v[146:149], v[38:41]
	v_mfma_f32_16x16x32_bf16 v[34:37], v[78:81], v[146:149], v[34:37]
	ds_read_b128 v[142:145], v188 offset:38912
	global_load_lds_dwordx4 v155, s[2:3]
	s_add_u32 m0, s8, 0x2000
	s_waitcnt lgkmcnt(5)
	v_mfma_f32_16x16x32_bf16 v[30:33], v[66:69], v[150:153], v[30:33]
	v_mfma_f32_16x16x32_bf16 v[26:29], v[70:73], v[150:153], v[26:29]
	v_mfma_f32_16x16x32_bf16 v[22:25], v[74:77], v[150:153], v[22:25]
	v_mfma_f32_16x16x32_bf16 v[18:21], v[78:81], v[150:153], v[18:21]
	ds_read_b128 v[146:149], v189 offset:32768
	global_load_lds_dwordx4 v156, s[2:3]
	s_add_u32 m0, s8, 0x3000
	s_waitcnt lgkmcnt(1)
	v_mfma_f32_16x16x32_bf16 v[14:17], v[66:69], v[142:145], v[14:17]
	v_mfma_f32_16x16x32_bf16 v[10:13], v[70:73], v[142:145], v[10:13]
	v_mfma_f32_16x16x32_bf16 v[6:9], v[74:77], v[142:145], v[6:9]
	v_mfma_f32_16x16x32_bf16 v[2:5], v[78:81], v[142:145], v[2:5]
	ds_read_b128 v[150:153], v189 offset:34816
	global_load_lds_dwordx4 v157, s[2:3]
	s_add_u32 m0, s8, 0x4000
	s_waitcnt lgkmcnt(1)
	v_mfma_f32_16x16x32_bf16 v[62:65], v[82:85], v[146:149], v[62:65]
	v_mfma_f32_16x16x32_bf16 v[58:61], v[86:89], v[146:149], v[58:61]
	v_mfma_f32_16x16x32_bf16 v[54:57], v[90:93], v[146:149], v[54:57]
	v_mfma_f32_16x16x32_bf16 v[50:53], v[94:97], v[146:149], v[50:53]
	ds_read_b128 v[142:145], v189 offset:36864
	global_load_lds_dwordx4 v158, s[6:7]
	s_add_u32 m0, s8, 0x5000
	s_waitcnt lgkmcnt(1)
	v_mfma_f32_16x16x32_bf16 v[46:49], v[82:85], v[150:153], v[46:49]
	v_mfma_f32_16x16x32_bf16 v[42:45], v[86:89], v[150:153], v[42:45]
	v_mfma_f32_16x16x32_bf16 v[38:41], v[90:93], v[150:153], v[38:41]
	v_mfma_f32_16x16x32_bf16 v[34:37], v[94:97], v[150:153], v[34:37]
	ds_read_b128 v[146:149], v189 offset:38912
	global_load_lds_dwordx4 v159, s[6:7]
	s_add_u32 m0, s8, 0x6000
	s_waitcnt lgkmcnt(1)
	v_mfma_f32_16x16x32_bf16 v[30:33], v[82:85], v[142:145], v[30:33]
	v_mfma_f32_16x16x32_bf16 v[26:29], v[86:89], v[142:145], v[26:29]
	v_mfma_f32_16x16x32_bf16 v[22:25], v[90:93], v[142:145], v[22:25]
	v_mfma_f32_16x16x32_bf16 v[18:21], v[94:97], v[142:145], v[18:21]
	global_load_lds_dwordx4 v160, s[6:7]
	s_add_u32 m0, s8, 0x7000
	s_waitcnt lgkmcnt(0)
	v_mfma_f32_16x16x32_bf16 v[14:17], v[82:85], v[146:149], v[14:17]
	v_mfma_f32_16x16x32_bf16 v[10:13], v[86:89], v[146:149], v[10:13]
	v_mfma_f32_16x16x32_bf16 v[6:9], v[90:93], v[146:149], v[6:9]
	v_mfma_f32_16x16x32_bf16 v[2:5], v[94:97], v[146:149], v[2:5]
	global_load_lds_dwordx4 v161, s[6:7]
	s_add_u32 s2, s2, 0x80
	s_addc_u32 s3, s3, 0
	s_add_u32 s6, s6, 0x80
	s_addc_u32 s7, s7, 0
	s_waitcnt vmcnt(0) lgkmcnt(0)
	s_barrier
	s_movk_i32 s9, 2
.Lm3_loop:
	ds_read_b128 v[66:69], v190 offset:16384
	ds_read_b128 v[70:73], v190 offset:18432
	ds_read_b128 v[74:77], v190 offset:20480
	ds_read_b128 v[78:81], v190 offset:22528
	ds_read_b128 v[142:145], v188
	ds_read_b128 v[146:149], v188 offset:2048
	s_add_u32 m0, s8, 0x8000
	s_waitcnt lgkmcnt(1)
	v_mfma_f32_16x16x32_bf16 v[62:65], v[66:69], v[142:145], v[62:65]
	v_mfma_f32_16x16x32_bf16 v[58:61], v[70:73], v[142:145], v[58:61]
	v_mfma_f32_16x16x32_bf16 v[54:57], v[74:77], v[142:145], v[54:57]
	v_mfma_f32_16x16x32_bf16 v[50:53], v[78:81], v[142:145], v[50:53]
	ds_read_b128 v[150:153], v188 offset:4096
	ds_read_b128 v[82:85], v191 offset:16384
	ds_read_b128 v[86:89], v191 offset:18432
	ds_read_b128 v[90:93], v191 offset:20480
	ds_read_b128 v[94:97], v191 offset:22528
	global_load_lds_dwordx4 v154, s[2:3]
	s_add_u32 m0, s8, 0x9000
	s_waitcnt lgkmcnt(5)
	v_mfma_f32_16x16x32_bf16 v[46:49], v[66:69], v[146:149], v[46:49]
	v_mfma_f32_16x16x32_bf16 v[42:45], v[70:73], v[146:149], v[42:45]
	v_mfma_f32_16x16x32_bf16 v[38:41], v[74:77], v[146:149], v[38:41]
	v_mfma_f32_16x16x32_bf16 v[34:37], v[78:81], v[146:149], v[34:37]
	ds_read_b128 v[142:145], v188 offset:6144
	global_load_lds_dwordx4 v155, s[2:3]
	s_add_u32 m0, s8, 0xa000
	s_waitcnt lgkmcnt(5)
	v_mfma_f32_16x16x32_bf16 v[30:33], v[66:69], v[150:153], v[30:33]
	v_mfma_f32_16x16x32_bf16 v[26:29], v[70:73], v[150:153], v[26:29]
	v_mfma_f32_16x16x32_bf16 v[22:25], v[74:77], v[150:153], v[22:25]
	v_mfma_f32_16x16x32_bf16 v[18:21], v[78:81], v[150:153], v[18:21]
	ds_read_b128 v[146:149], v189
	global_load_lds_dwordx4 v156, s[2:3]
	s_add_u32 m0, s8, 0xb000
	s_waitcnt lgkmcnt(1)
	v_mfma_f32_16x16x32_bf16 v[14:17], v[66:69], v[142:145], v[14:17]
	v_mfma_f32_16x16x32_bf16 v[10:13], v[70:73], v[142:145], v[10:13]
	v_mfma_f32_16x16x32_bf16 v[6:9], v[74:77], v[142:145], v[6:9]
	v_mfma_f32_16x16x32_bf16 v[2:5], v[78:81], v[142:145], v[2:5]
	ds_read_b128 v[150:153], v189 offset:2048
	global_load_lds_dwordx4 v157, s[2:3]
	s_add_u32 m0, s8, 0xc000
	s_waitcnt lgkmcnt(1)
	v_mfma_f32_16x16x32_bf16 v[62:65], v[82:85], v[146:149], v[62:65]
	v_mfma_f32_16x16x32_bf16 v[58:61], v[86:89], v[146:149], v[58:61]
	v_mfma_f32_16x16x32_bf16 v[54:57], v[90:93], v[146:149], v[54:57]
	v_mfma_f32_16x16x32_bf16 v[50:53], v[94:97], v[146:149], v[50:53]
	ds_read_b128 v[142:145], v189 offset:4096
	global_load_lds_dwordx4 v158, s[6:7]
	s_add_u32 m0, s8, 0xd000
	s_waitcnt lgkmcnt(1)
	v_mfma_f32_16x16x32_bf16 v[46:49], v[82:85], v[150:153], v[46:49]
	v_mfma_f32_16x16x32_bf16 v[42:45], v[86:89], v[150:153], v[42:45]
	v_mfma_f32_16x16x32_bf16 v[38:41], v[90:93], v[150:153], v[38:41]
	v_mfma_f32_16x16x32_bf16 v[34:37], v[94:97], v[150:153], v[34:37]
	ds_read_b128 v[146:149], v189 offset:6144
	global_load_lds_dwordx4 v159, s[6:7]
	s_add_u32 m0, s8, 0xe000
	s_waitcnt lgkmcnt(1)
	v_mfma_f32_16x16x32_bf16 v[30:33], v[82:85], v[142:145], v[30:33]
	v_mfma_f32_16x16x32_bf16 v[26:29], v[86:89], v[142:145], v[26:29]
	v_mfma_f32_16x16x32_bf16 v[22:25], v[90:93], v[142:145], v[22:25]
	v_mfma_f32_16x16x32_bf16 v[18:21], v[94:97], v[142:145], v[18:21]
	global_load_lds_dwordx4 v160, s[6:7]
	s_add_u32 m0, s8, 0xf000
	s_waitcnt lgkmcnt(0)
	v_mfma_f32_16x16x32_bf16 v[14:17], v[82:85], v[146:149], v[14:17]
	v_mfma_f32_16x16x32_bf16 v[10:13], v[86:89], v[146:149], v[10:13]
	v_mfma_f32_16x16x32_bf16 v[6:9], v[90:93], v[146:149], v[6:9]
	v_mfma_f32_16x16x32_bf16 v[2:5], v[94:97], v[146:149], v[2:5]
	global_load_lds_dwordx4 v161, s[6:7]
	s_add_u32 s2, s2, 0x80
	s_addc_u32 s3, s3, 0
	s_add_u32 s6, s6, 0x80
	s_addc_u32 s7, s7, 0
	s_waitcnt vmcnt(0) lgkmcnt(0)
	s_barrier
	ds_read_b128 v[66:69], v190 offset:49152
	ds_read_b128 v[70:73], v190 offset:51200
	ds_read_b128 v[74:77], v190 offset:53248
	ds_read_b128 v[78:81], v190 offset:55296
	ds_read_b128 v[142:145], v188 offset:32768
	ds_read_b128 v[146:149], v188 offset:34816
	s_mov_b32 m0, s8
	s_waitcnt lgkmcnt(1)
	v_mfma_f32_16x16x32_bf16 v[62:65], v[66:69], v[142:145], v[62:65]
	v_mfma_f32_16x16x32_bf16 v[58:61], v[70:73], v[142:145], v[58:61]
	v_mfma_f32_16x16x32_bf16 v[54:57], v[74:77], v[142:145], v[54:57]
	v_mfma_f32_16x16x32_bf16 v[50:53], v[78:81], v[142:145], v[50:53]
	ds_read_b128 v[150:153], v188 offset:36864
	ds_read_b128 v[82:85], v191 offset:49152
	ds_read_b128 v[86:89], v191 offset:51200
	ds_read_b128 v[90:93], v191 offset:53248
	ds_read_b128 v[94:97], v191 offset:55296
	global_load_lds_dwordx4 v154, s[2:3]
	s_add_u32 m0, s8, 0x1000
	s_waitcnt lgkmcnt(5)
	v_mfma_f32_16x16x32_bf16 v[46:49], v[66:69], v[146:149], v[46:49]
	v_mfma_f32_16x16x32_bf16 v[42:45], v[70:73], v[146:149], v[42:45]
	v_mfma_f32_16x16x32_bf16 v[38:41], v[74:77], v[146:149], v[38:41]
	v_mfma_f32_16x16x32_bf16 v[34:37], v[78:81], v[146:149], v[34:37]
	ds_read_b128 v[142:145], v188 offset:38912
	global_load_lds_dwordx4 v155, s[2:3]
	s_add_u32 m0, s8, 0x2000
	s_waitcnt lgkmcnt(5)
	v_mfma_f32_16x16x32_bf16 v[30:33], v[66:69], v[150:153], v[30:33]
	v_mfma_f32_16x16x32_bf16 v[26:29], v[70:73], v[150:153], v[26:29]
	v_mfma_f32_16x16x32_bf16 v[22:25], v[74:77], v[150:153], v[22:25]
	v_mfma_f32_16x16x32_bf16 v[18:21], v[78:81], v[150:153], v[18:21]
	ds_read_b128 v[146:149], v189 offset:32768
	global_load_lds_dwordx4 v156, s[2:3]
	s_add_u32 m0, s8, 0x3000
	s_waitcnt lgkmcnt(1)
	v_mfma_f32_16x16x32_bf16 v[14:17], v[66:69], v[142:145], v[14:17]
	v_mfma_f32_16x16x32_bf16 v[10:13], v[70:73], v[142:145], v[10:13]
	v_mfma_f32_16x16x32_bf16 v[6:9], v[74:77], v[142:145], v[6:9]
	v_mfma_f32_16x16x32_bf16 v[2:5], v[78:81], v[142:145], v[2:5]
	ds_read_b128 v[150:153], v189 offset:34816
	global_load_lds_dwordx4 v157, s[2:3]
	s_add_u32 m0, s8, 0x4000
	s_waitcnt lgkmcnt(1)
	v_mfma_f32_16x16x32_bf16 v[62:65], v[82:85], v[146:149], v[62:65]
	v_mfma_f32_16x16x32_bf16 v[58:61], v[86:89], v[146:149], v[58:61]
	v_mfma_f32_16x16x32_bf16 v[54:57], v[90:93], v[146:149], v[54:57]
	v_mfma_f32_16x16x32_bf16 v[50:53], v[94:97], v[146:149], v[50:53]
	ds_read_b128 v[142:145], v189 offset:36864
	global_load_lds_dwordx4 v158, s[6:7]
	s_add_u32 m0, s8, 0x5000
	s_waitcnt lgkmcnt(1)
	v_mfma_f32_16x16x32_bf16 v[46:49], v[82:85], v[150:153], v[46:49]
	v_mfma_f32_16x16x32_bf16 v[42:45], v[86:89], v[150:153], v[42:45]
	v_mfma_f32_16x16x32_bf16 v[38:41], v[90:93], v[150:153], v[38:41]
	v_mfma_f32_16x16x32_bf16 v[34:37], v[94:97], v[150:153], v[34:37]
	ds_read_b128 v[146:149], v189 offset:38912
	global_load_lds_dwordx4 v159, s[6:7]
	s_add_u32 m0, s8, 0x6000
	s_waitcnt lgkmcnt(1)
	v_mfma_f32_16x16x32_bf16 v[30:33], v[82:85], v[142:145], v[30:33]
	v_mfma_f32_16x16x32_bf16 v[26:29], v[86:89], v[142:145], v[26:29]
	v_mfma_f32_16x16x32_bf16 v[22:25], v[90:93], v[142:145], v[22:25]
	v_mfma_f32_16x16x32_bf16 v[18:21], v[94:97], v[142:145], v[18:21]
	global_load_lds_dwordx4 v160, s[6:7]
	s_add_u32 m0, s8, 0x7000
	s_waitcnt lgkmcnt(0)
	v_mfma_f32_16x16x32_bf16 v[14:17], v[82:85], v[146:149], v[14:17]
	v_mfma_f32_16x16x32_bf16 v[10:13], v[86:89], v[146:149], v[10:13]
	v_mfma_f32_16x16x32_bf16 v[6:9], v[90:93], v[146:149], v[6:9]
	v_mfma_f32_16x16x32_bf16 v[2:5], v[94:97], v[146:149], v[2:5]
	global_load_lds_dwordx4 v161, s[6:7]
	s_add_u32 s2, s2, 0x80
	s_addc_u32 s3, s3, 0
	s_add_u32 s6, s6, 0x80
	s_addc_u32 s7, s7, 0
	s_add_i32 s9, s9, -1
	s_waitcnt vmcnt(0) lgkmcnt(0)
	s_barrier
	s_cmp_lg_u32 s9, 0
	s_cbranch_scc1 .Lm3_loop
	ds_read_b128 v[66:69], v190 offset:16384
	ds_read_b128 v[70:73], v190 offset:18432
	ds_read_b128 v[74:77], v190 offset:20480
	ds_read_b128 v[78:81], v190 offset:22528
	ds_read_b128 v[142:145], v188
	ds_read_b128 v[146:149], v188 offset:2048
	s_add_u32 m0, s8, 0x8000
	s_waitcnt lgkmcnt(1)
	v_mfma_f32_16x16x32_bf16 v[62:65], v[66:69], v[142:145], v[62:65]
	v_mfma_f32_16x16x32_bf16 v[58:61], v[70:73], v[142:145], v[58:61]
	v_mfma_f32_16x16x32_bf16 v[54:57], v[74:77], v[142:145], v[54:57]
	v_mfma_f32_16x16x32_bf16 v[50:53], v[78:81], v[142:145], v[50:53]
	ds_read_b128 v[150:153], v188 offset:4096
	ds_read_b128 v[82:85], v191 offset:16384
	ds_read_b128 v[86:89], v191 offset:18432
	ds_read_b128 v[90:93], v191 offset:20480
	ds_read_b128 v[94:97], v191 offset:22528
	global_load_lds_dwordx4 v154, s[2:3]
	s_add_u32 m0, s8, 0x9000
	s_waitcnt lgkmcnt(5)
	v_mfma_f32_16x16x32_bf16 v[46:49], v[66:69], v[146:149], v[46:49]
	v_mfma_f32_16x16x32_bf16 v[42:45], v[70:73], v[146:149], v[42:45]
	v_mfma_f32_16x16x32_bf16 v[38:41], v[74:77], v[146:149], v[38:41]
	v_mfma_f32_16x16x32_bf16 v[34:37], v[78:81], v[146:149], v[34:37]
	ds_read_b128 v[142:145], v188 offset:6144
	global_load_lds_dwordx4 v155, s[2:3]
	s_add_u32 m0, s8, 0xa000
	s_waitcnt lgkmcnt(5)
	v_mfma_f32_16x16x32_bf16 v[30:33], v[66:69], v[150:153], v[30:33]
	v_mfma_f32_16x16x32_bf16 v[26:29], v[70:73], v[150:153], v[26:29]
	v_mfma_f32_16x16x32_bf16 v[22:25], v[74:77], v[150:153], v[22:25]
	v_mfma_f32_16x16x32_bf16 v[18:21], v[78:81], v[150:153], v[18:21]
	ds_read_b128 v[146:149], v189
	global_load_lds_dwordx4 v156, s[2:3]
	s_add_u32 m0, s8, 0xb000
	s_waitcnt lgkmcnt(1)
	v_mfma_f32_16x16x32_bf16 v[14:17], v[66:69], v[142:145], v[14:17]
	v_mfma_f32_16x16x32_bf16 v[10:13], v[70:73], v[142:145], v[10:13]
	v_mfma_f32_16x16x32_bf16 v[6:9], v[74:77], v[142:145], v[6:9]
	v_mfma_f32_16x16x32_bf16 v[2:5], v[78:81], v[142:145], v[2:5]
	ds_read_b128 v[150:153], v189 offset:2048
	global_load_lds_dwordx4 v157, s[2:3]
	s_add_u32 m0, s8, 0xc000
	s_waitcnt lgkmcnt(1)
	v_mfma_f32_16x16x32_bf16 v[62:65], v[82:85], v[146:149], v[62:65]
	v_mfma_f32_16x16x32_bf16 v[58:61], v[86:89], v[146:149], v[58:61]
	v_mfma_f32_16x16x32_bf16 v[54:57], v[90:93], v[146:149], v[54:57]
	v_mfma_f32_16x16x32_bf16 v[50:53], v[94:97], v[146:149], v[50:53]
	ds_read_b128 v[142:145], v189 offset:4096
	global_load_lds_dwordx4 v158, s[6:7]
	s_add_u32 m0, s8, 0xd000
	s_waitcnt lgkmcnt(1)
	v_mfma_f32_16x16x32_bf16 v[46:49], v[82:85], v[150:153], v[46:49]
	v_mfma_f32_16x16x32_bf16 v[42:45], v[86:89], v[150:153], v[42:45]
	v_mfma_f32_16x16x32_bf16 v[38:41], v[90:93], v[150:153], v[38:41]
	v_mfma_f32_16x16x32_bf16 v[34:37], v[94:97], v[150:153], v[34:37]
	ds_read_b128 v[146:149], v189 offset:6144
	global_load_lds_dwordx4 v159, s[6:7]
	s_add_u32 m0, s8, 0xe000
	s_waitcnt lgkmcnt(1)
	v_mfma_f32_16x16x32_bf16 v[30:33], v[82:85], v[142:145], v[30:33]
	v_mfma_f32_16x16x32_bf16 v[26:29], v[86:89], v[142:145], v[26:29]
	v_mfma_f32_16x16x32_bf16 v[22:25], v[90:93], v[142:145], v[22:25]
	v_mfma_f32_16x16x32_bf16 v[18:21], v[94:97], v[142:145], v[18:21]
	global_load_lds_dwordx4 v160, s[6:7]
	s_add_u32 m0, s8, 0xf000
	s_waitcnt lgkmcnt(0)
	v_mfma_f32_16x16x32_bf16 v[14:17], v[82:85], v[146:149], v[14:17]
	v_mfma_f32_16x16x32_bf16 v[10:13], v[86:89], v[146:149], v[10:13]
	v_mfma_f32_16x16x32_bf16 v[6:9], v[90:93], v[146:149], v[6:9]
	v_mfma_f32_16x16x32_bf16 v[2:5], v[94:97], v[146:149], v[2:5]
	global_load_lds_dwordx4 v161, s[6:7]
	s_add_u32 s2, s2, 0x80
	s_addc_u32 s3, s3, 0
	s_add_u32 s6, s6, 0x80
	s_addc_u32 s7, s7, 0
	s_waitcnt vmcnt(0) lgkmcnt(0)
	s_barrier
	ds_read_b128 v[66:69], v190 offset:49152
	ds_read_b128 v[70:73], v190 offset:51200
	ds_read_b128 v[74:77], v190 offset:53248
	ds_read_b128 v[78:81], v190 offset:55296
	ds_read_b128 v[142:145], v188 offset:32768
	ds_read_b128 v[146:149], v188 offset:34816
	s_waitcnt lgkmcnt(1)
	v_mfma_f32_16x16x32_bf16 v[62:65], v[66:69], v[142:145], v[62:65]
	v_mfma_f32_16x16x32_bf16 v[58:61], v[70:73], v[142:145], v[58:61]
	v_mfma_f32_16x16x32_bf16 v[54:57], v[74:77], v[142:145], v[54:57]
	v_mfma_f32_16x16x32_bf16 v[50:53], v[78:81], v[142:145], v[50:53]
	ds_read_b128 v[150:153], v188 offset:36864
	ds_read_b128 v[82:85], v191 offset:49152
	ds_read_b128 v[86:89], v191 offset:51200
	ds_read_b128 v[90:93], v191 offset:53248
	ds_read_b128 v[94:97], v191 offset:55296
	s_waitcnt lgkmcnt(5)
	v_mfma_f32_16x16x32_bf16 v[46:49], v[66:69], v[146:149], v[46:49]
	v_mfma_f32_16x16x32_bf16 v[42:45], v[70:73], v[146:149], v[42:45]
	v_mfma_f32_16x16x32_bf16 v[38:41], v[74:77], v[146:149], v[38:41]
	v_mfma_f32_16x16x32_bf16 v[34:37], v[78:81], v[146:149], v[34:37]
	ds_read_b128 v[142:145], v188 offset:38912
	s_waitcnt lgkmcnt(5)
	v_mfma_f32_16x16x32_bf16 v[30:33], v[66:69], v[150:153], v[30:33]
	v_mfma_f32_16x16x32_bf16 v[26:29], v[70:73], v[150:153], v[26:29]
	v_mfma_f32_16x16x32_bf16 v[22:25], v[74:77], v[150:153], v[22:25]
	v_mfma_f32_16x16x32_bf16 v[18:21], v[78:81], v[150:153], v[18:21]
	ds_read_b128 v[146:149], v189 offset:32768
	s_waitcnt lgkmcnt(1)
	v_mfma_f32_16x16x32_bf16 v[14:17], v[66:69], v[142:145], v[14:17]
	v_mfma_f32_16x16x32_bf16 v[10:13], v[70:73], v[142:145], v[10:13]
	v_mfma_f32_16x16x32_bf16 v[6:9], v[74:77], v[142:145], v[6:9]
	v_mfma_f32_16x16x32_bf16 v[2:5], v[78:81], v[142:145], v[2:5]
	ds_read_b128 v[150:153], v189 offset:34816
	s_waitcnt lgkmcnt(1)
	v_mfma_f32_16x16x32_bf16 v[62:65], v[82:85], v[146:149], v[62:65]
	v_mfma_f32_16x16x32_bf16 v[58:61], v[86:89], v[146:149], v[58:61]
	v_mfma_f32_16x16x32_bf16 v[54:57], v[90:93], v[146:149], v[54:57]
	v_mfma_f32_16x16x32_bf16 v[50:53], v[94:97], v[146:149], v[50:53]
	ds_read_b128 v[142:145], v189 offset:36864
	s_waitcnt lgkmcnt(1)
	v_mfma_f32_16x16x32_bf16 v[46:49], v[82:85], v[150:153], v[46:49]
	v_mfma_f32_16x16x32_bf16 v[42:45], v[86:89], v[150:153], v[42:45]
	v_mfma_f32_16x16x32_bf16 v[38:41], v[90:93], v[150:153], v[38:41]
	v_mfma_f32_16x16x32_bf16 v[34:37], v[94:97], v[150:153], v[34:37]
	ds_read_b128 v[146:149], v189 offset:38912
	s_waitcnt lgkmcnt(1)
	v_mfma_f32_16x16x32_bf16 v[30:33], v[82:85], v[142:145], v[30:33]
	v_mfma_f32_16x16x32_bf16 v[26:29], v[86:89], v[142:145], v[26:29]
	v_mfma_f32_16x16x32_bf16 v[22:25], v[90:93], v[142:145], v[22:25]
	v_mfma_f32_16x16x32_bf16 v[18:21], v[94:97], v[142:145], v[18:21]
	s_waitcnt lgkmcnt(0)
	v_mfma_f32_16x16x32_bf16 v[14:17], v[82:85], v[146:149], v[14:17]
	v_mfma_f32_16x16x32_bf16 v[10:13], v[86:89], v[146:149], v[10:13]
	v_mfma_f32_16x16x32_bf16 v[6:9], v[90:93], v[146:149], v[6:9]
	v_mfma_f32_16x16x32_bf16 v[2:5], v[94:97], v[146:149], v[2:5]
	s_waitcnt lgkmcnt(0)
	s_barrier
	s_nop 7
	s_nop 2
	s_movk_i32 s92, 0x480
	s_branch .LBB0_111
